# stacked attention trims: constant lane masks + scalar-base DMA addresses + no compiler DMA waits + row-sum seed add (0 + p) dropped
# speedup vs baseline: 1.0077x; 1.0060x over previous
; #define LAS __attribute__((address_space(3)))
; __device__ __forceinline__ s16x4 vtr(LAS const unsigned char* p) { return __builtin_bit_cast(s16x4, __builtin_amdgcn_ds_read_tr16_b64_v4i16((LAS v4i16_t*)p)); }
; __device__ __forceinline__ void att_block(const bf16x8 (&kf)[4], const bf16x8 (&qf)[4], const bf16x8 (&va)[4], f32x16& o0, f32x16& o1, float& mrun, float& lrun, bool domask, int lo_, int hi_) {
;     ...
;     for (int kk = 0; kk < 4; ++kk) st = __builtin_amdgcn_mfma_f32_32x32x16_bf16(kf[kk], qf[kk], st, 0, 0, 0);
;     if (domask) {
;         asm volatile("" : "+v"(lo_), "+v"(hi_));
; #pragma unroll
;         for (int i = 0; i < 16; ++i) { const int ci = (i & 3) + 8 * (i >> 2); st[i] = ((ci - lo_) | (hi_ - ci)) < 0 ? -INFINITY : st[i]; }
;     }
; __device__ __forceinline__ void att_phase(unsigned char* ws, LAS unsigned char* lds, int lane, int wave, int G) {
;     ...
;             asm volatile("s_waitcnt vmcnt(0)" ::: "memory");
;             if (kb < 5) ATT_DMA_KV(P, kb + 1, sb ^ 1);
;             else if (hn) ATT_DMA_KV(N, 0, sb ^ 1);
;             bf16x8 kf[4], va[4];
; #pragma unroll
;             for (int kk = 0; kk < 4; ++kk) kf[kk] = *(LAS const bf16x8*)(kfb + sb * 4096 + (((2 * kk + h) ^ (qc & 7)) << 4));
;             LAS const unsigned char* trs = trb + 8192 + sb * 4096;
; #pragma unroll
;             for (int s = 0; s < 2; ++s) {
;                 const s16x4 lo0 = vtr(trs + (16 * s) * VP), hi0 = vtr(trs + (16 * s + 8) * VP);
;                 const s16x4 lo1 = vtr(trs + (16 * s) * VP + 64), hi1 = vtr(trs + (16 * s + 8) * VP + 64);
;                 va[2 * s] = (bf16x8){lo0[0], lo0[1], lo0[2], lo0[3], hi0[0], hi0[1], hi0[2], hi0[3]};
;                 va[2 * s + 1] = (bf16x8){lo1[0], lo1[1], lo1[2], lo1[3], hi1[0], hi1[1], hi1[2], hi1[3]};
;             }
;             if (kb <= 4) {
;                 att_block(kf, qfA, va, oA0, oA1, mA, lA, kb == 0 || kb == 4 || kminA > 32 * kb, mloA - 4 * h - 32 * kb, qc + 128 - 4 * h - 32 * kb);
.LBB0_80:
	v_add_u32_e32 v0, 0xffffffa0, v191
	v_mul_lo_u32 v0, s56, v0
	v_add_u32_e32 v4, s11, v0
	v_max_i32_e32 v164, 0, v4
	s_add_i32 s57, s33, 0x1000
	s_lshl_b32 s6, s56, 3
	s_waitcnt vmcnt(0)
	v_lshl_add_u32 v2, v164, 7, v180
	s_mov_b32 m0, s57
	s_add_i32 s7, s33, 0x3000
	v_add_u32_e32 v4, s6, v4
	global_load_lds_dwordx4 v2, s[98:99]
	v_lshl_add_u32 v0, v164, 7, v182
	s_mov_b32 m0, s7
	v_max_i32_e32 v164, 0, v4
	global_load_lds_dwordx4 v0, s[100:101]
	v_readlane_b32 s15, v254, 28
	v_lshl_add_u32 v2, v164, 7, v180
	s_mov_b32 m0, s15
	v_readlane_b32 s15, v254, 29
	v_add_u32_e32 v4, s6, v4
	global_load_lds_dwordx4 v2, s[98:99]
	v_lshl_add_u32 v0, v164, 7, v182
	s_mov_b32 m0, s15
	v_max_i32_e32 v164, 0, v4
	global_load_lds_dwordx4 v0, s[100:101]
	s_add_i32 s15, s33, 0x1800
	v_lshl_add_u32 v2, v164, 7, v180
	s_mov_b32 m0, s15
	s_add_i32 s17, s33, 0x3800
	v_add_u32_e32 v51, s6, v4
	global_load_lds_dwordx4 v2, s[98:99]
	v_lshl_add_u32 v0, v164, 7, v182
	s_mov_b32 m0, s17
	v_max_i32_e32 v164, 0, v51
	global_load_lds_dwordx4 v0, s[100:101]
	s_add_i32 s21, s33, 0x1c00
	v_lshl_add_u32 v2, v164, 7, v180
	s_mov_b32 m0, s21
	v_readlane_b32 s59, v254, 30
	global_load_lds_dwordx4 v2, s[98:99]
	v_lshl_add_u32 v0, v164, 7, v182
	s_mov_b32 m0, s59
	v_max_i32_e32 v199, s58, v189
	global_load_lds_dwordx4 v0, s[100:101]
	ds_read_b128 v[0:3], v225
	ds_read_b128 v[16:19], v226
	s_waitcnt lgkmcnt(0)
	v_mfma_f32_32x32x16_bf16 v[0:15], v[0:3], v[128:131], 0
	ds_read_b128 v[20:23], v228
	s_mov_b32 s59, 0xff800000
	v_mfma_f32_32x32x16_bf16 v[0:15], v[16:19], v[124:127], v[0:15]
	ds_read_b128 v[16:19], v227
	ds_read_b64_tr_b16 v[34:35], v229 offset:8192
	ds_read_b64_tr_b16 v[36:37], v229 offset:9216
	ds_read_b64_tr_b16 v[40:41], v229 offset:9280
	ds_read_b64_tr_b16 v[38:39], v229 offset:8256
	ds_read_b64_tr_b16 v[42:43], v229 offset:10240
	ds_read_b64_tr_b16 v[44:45], v229 offset:11264
	ds_read_b64_tr_b16 v[48:49], v229 offset:11328
	ds_read_b64_tr_b16 v[46:47], v229 offset:10304
	s_waitcnt lgkmcnt(8)
	v_mfma_f32_32x32x16_bf16 v[0:15], v[16:19], v[120:123], v[0:15]
	v_sub_u32_e32 v16, v199, v193
	v_mov_b32_e32 v17, v214
	s_waitcnt lgkmcnt(0)
	s_nop 0
	v_mfma_f32_32x32x16_bf16 v[0:15], v[20:23], v[116:119], v[0:15]
	s_nop 6
	s_cmp_lg_u32 s58, 0
	s_cbranch_scc1 .Lmk_slow_0
	s_mov_b32 vcc_lo, 0x1
	s_mov_b32 vcc_hi, 0x1f
	s_mov_b32 s24, 0x3
	s_mov_b32 s25, 0x3f
	s_mov_b32 s26, 0x7
	s_mov_b32 s27, 0x7f
	s_mov_b32 s28, 0xf
	s_mov_b32 s29, 0xff
	s_nop 0
	v_cndmask_b32_e32 v0, v211, v0, vcc
	s_mov_b32 vcc_lo, 0x1ff
	s_mov_b32 vcc_hi, 0x1fff
	v_cndmask_b32_e64 v1, v211, v1, s[24:25]
	s_mov_b32 s24, 0x3ff
	s_mov_b32 s25, 0x3fff
	v_cndmask_b32_e64 v2, v211, v2, s[26:27]
	s_mov_b32 s26, 0x7ff
	s_mov_b32 s27, 0x7fff
	v_cndmask_b32_e64 v3, v211, v3, s[28:29]
	s_mov_b32 s28, 0xfff
	s_mov_b32 s29, 0xffff
	v_cndmask_b32_e32 v4, v211, v4, vcc
	s_mov_b32 vcc_lo, 0x1ffff
	s_mov_b32 vcc_hi, 0x1fffff
	v_cndmask_b32_e64 v5, v211, v5, s[24:25]
	s_mov_b32 s24, 0x3ffff
	s_mov_b32 s25, 0x3fffff
	v_cndmask_b32_e64 v6, v211, v6, s[26:27]
	s_mov_b32 s26, 0x7ffff
	s_mov_b32 s27, 0x7fffff
	v_cndmask_b32_e64 v7, v211, v7, s[28:29]
	s_mov_b32 s28, 0xfffff
	s_mov_b32 s29, 0xffffff
	v_cndmask_b32_e32 v8, v211, v8, vcc
	s_mov_b32 vcc_lo, 0x1ffffff
	s_mov_b32 vcc_hi, 0x1fffffff
	v_cndmask_b32_e64 v9, v211, v9, s[24:25]
	s_mov_b32 s24, 0x3ffffff
	s_mov_b32 s25, 0x3fffffff
	v_cndmask_b32_e64 v10, v211, v10, s[26:27]
	s_mov_b32 s26, 0x7ffffff
	s_mov_b32 s27, 0x7fffffff
	v_cndmask_b32_e64 v11, v211, v11, s[28:29]
	s_mov_b32 s28, 0xfffffff
	s_mov_b32 s29, 0xffffffff
	v_cndmask_b32_e32 v56, v211, v12, vcc
	v_cndmask_b32_e64 v57, v211, v13, s[24:25]
	v_cndmask_b32_e64 v58, v211, v14, s[26:27]
	v_cndmask_b32_e64 v59, v211, v15, s[28:29]
	s_branch .Lmk_done_0

; #define LAS __attribute__((address_space(3)))
; __device__ __forceinline__ void att_block(const bf16x8 (&kf)[4], const bf16x8 (&qf)[4], const bf16x8 (&va)[4], f32x16& o0, f32x16& o1, float& mrun, float& lrun, bool domask, int lo_, int hi_) {
;     ...
;     float bmax = -INFINITY;
; #pragma unroll
;     for (int i = 0; i < 16; ++i) bmax = fmaxf(bmax, st[i]);
;     bmax = fmaxf(bmax, __shfl_xor(bmax, 32));
;     const float mnew = fmaxf(mrun, bmax);
;     float lsum = 0.f;
; #pragma unroll
;     for (int i = 0; i < 16; ++i) { st[i] = __builtin_amdgcn_exp2f(st[i] - mnew); lsum += st[i]; }
;     lsum += __shfl_xor(lsum, 32);
;     const float alpha = __builtin_amdgcn_exp2f(mrun - mnew);
;     lrun = lrun * alpha + lsum; mrun = mnew;
; #pragma unroll
;     for (int i = 0; i < 16; ++i) { o0[i] *= alpha; o1[i] *= alpha; }
; #pragma unroll
;     for (int s = 0; s < 2; ++s) { v4u w; w.x = pk2(st[8 * s], st[8 * s + 1]); w.y = pk2(st[8 * s + 2], st[8 * s + 3]); w.z = pk2(st[8 * s + 4], st[8 * s + 5]); w.w = pk2(st[8 * s + 6], st[8 * s + 7]);
;         const bf16x8 pb = __builtin_bit_cast(bf16x8, w);
;         o0 = __builtin_amdgcn_mfma_f32_32x32x16_bf16(va[2 * s], pb, o0, 0, 0, 0);
;         o1 = __builtin_amdgcn_mfma_f32_32x32x16_bf16(va[2 * s + 1], pb, o1, 0, 0, 0); }
; __device__ __forceinline__ void att_phase(unsigned char* ws, LAS unsigned char* lds, int lane, int wave, int G) {
;     ...
;             asm volatile("s_waitcnt vmcnt(0)" ::: "memory");
;             if (kb < 5) ATT_DMA_KV(P, kb + 1, sb ^ 1);
;             else if (hn) ATT_DMA_KV(N, 0, sb ^ 1);
;             bf16x8 kf[4], va[4];
; #pragma unroll
;             for (int kk = 0; kk < 4; ++kk) kf[kk] = *(LAS const bf16x8*)(kfb + sb * 4096 + (((2 * kk + h) ^ (qc & 7)) << 4));
;             LAS const unsigned char* trs = trb + 8192 + sb * 4096;
; #pragma unroll
;             for (int s = 0; s < 2; ++s) {
;                 const s16x4 lo0 = vtr(trs + (16 * s) * VP), hi0 = vtr(trs + (16 * s + 8) * VP);
;                 const s16x4 lo1 = vtr(trs + (16 * s) * VP + 64), hi1 = vtr(trs + (16 * s + 8) * VP + 64);
;                 va[2 * s] = (bf16x8){lo0[0], lo0[1], lo0[2], lo0[3], hi0[0], hi0[1], hi0[2], hi0[3]};
;                 va[2 * s + 1] = (bf16x8){lo1[0], lo1[1], lo1[2], lo1[3], hi1[0], hi1[1], hi1[2], hi1[3]};
;             }
;             if (kb <= 4) {
.Lmk_done_0:
	s_nop 0
	s_nop 0
	v_max3_f32 v12, v0, s59, v1
	v_max3_f32 v12, v12, v2, v3
	v_max3_f32 v12, v12, v4, v5
	v_max3_f32 v12, v12, v6, v7
	v_max3_f32 v12, v12, v8, v9
	v_xor_b32_e32 v13, 32, v206
	v_max3_f32 v12, v12, v10, v11
	v_cmp_lt_i32_e32 vcc, v13, v208
	v_max3_f32 v12, v12, v56, v57
	v_max3_f32 v12, v12, v58, v59
	v_cndmask_b32_e32 v13, v206, v13, vcc
	v_lshlrev_b32_e32 v201, 2, v13
	ds_bpermute_b32 v13, v201, v12
	s_mov_b32 s59, 0xf149f2ca
	s_waitcnt lgkmcnt(0)
	v_max3_f32 v50, v12, v13, s59
	v_sub_f32_e32 v0, v0, v50
	v_exp_f32_e32 v16, v0
	v_sub_f32_e32 v0, v1, v50
	v_exp_f32_e32 v17, v0
	v_sub_f32_e32 v1, v2, v50
	v_exp_f32_e32 v18, v1
	v_sub_f32_e32 v1, v3, v50
	v_exp_f32_e32 v19, v1
	v_sub_f32_e32 v1, v4, v50
	v_exp_f32_e32 v20, v1
	v_sub_f32_e32 v1, v5, v50
	v_add_f32_e32 v0, v17, v16
	v_exp_f32_e32 v21, v1
	v_sub_f32_e32 v1, v6, v50
	v_add_f32_e32 v0, v18, v0
	v_exp_f32_e32 v22, v1
	v_sub_f32_e32 v1, v7, v50
	v_add_f32_e32 v0, v19, v0
	v_exp_f32_e32 v23, v1
	v_sub_f32_e32 v1, v8, v50
	v_add_f32_e32 v0, v20, v0
	v_exp_f32_e32 v60, v1
	v_sub_f32_e32 v1, v9, v50
	v_add_f32_e32 v0, v21, v0
	v_exp_f32_e32 v61, v1
	v_add_f32_e32 v0, v22, v0
	v_add_f32_e32 v0, v23, v0
	v_add_f32_e32 v0, v60, v0
	v_add_f32_e32 v62, v61, v0
	v_sub_f32_e32 v1, v10, v50
	v_cvt_pk_bf16_f32 v52, v16, v17
	v_sub_f32_e32 v16, v56, v50
	v_mov_b32_e32 v0, 0
	v_exp_f32_e32 v63, v1
	v_sub_f32_e32 v64, v11, v50
	v_cvt_pk_bf16_f32 v53, v18, v19
	v_cvt_pk_bf16_f32 v54, v20, v21
	v_cvt_pk_bf16_f32 v55, v22, v23
	v_exp_f32_e32 v56, v16
	v_sub_f32_e32 v16, v57, v50
	v_mfma_f32_32x32x16_bf16 v[18:33], v[34:37], v[52:55], 0
	v_exp_f32_e32 v57, v16
	v_sub_f32_e32 v34, v58, v50
	v_exp_f32_e32 v64, v64
	v_cvt_pk_bf16_f32 v36, v56, v57
	s_nop 1
	v_exp_f32_e32 v1, v34
	v_sub_f32_e32 v34, v59, v50
	v_mfma_f32_32x32x16_bf16 v[2:17], v[38:41], v[52:55], 0
	v_exp_f32_e32 v38, v34
	v_add_f32_e32 v39, v63, v62
	v_add_f32_e32 v39, v64, v39
	v_cvt_pk_bf16_f32 v34, v60, v61
	v_cvt_pk_bf16_f32 v35, v63, v64
	v_cvt_pk_bf16_f32 v37, v1, v38
	v_add_f32_e32 v39, v56, v39
	v_add_f32_e32 v39, v57, v39
	v_mfma_f32_32x32x16_bf16 v[18:33], v[42:45], v[34:37], v[18:33]
	v_add_f32_e32 v1, v1, v39
	v_add_f32_e32 v1, v38, v1
	ds_bpermute_b32 v232, v201, v1
	v_mfma_f32_32x32x16_bf16 v[2:17], v[46:49], v[34:37], v[2:17]
	v_add_u32_e32 v38, s6, v51
	v_max_i32_e32 v164, 0, v38
	s_mov_b32 m0, s33
	s_waitcnt vmcnt(0)
	v_lshl_add_u32 v36, v164, 7, v180
	v_add_u32_e32 v38, s6, v38
	global_load_lds_dwordx4 v36, s[98:99]
	v_lshl_add_u32 v34, v164, 7, v182
	s_mov_b32 m0, s44
	v_max_i32_e32 v164, 0, v38
	global_load_lds_dwordx4 v34, s[100:101]
	v_lshl_add_u32 v36, v164, 7, v180
	s_mov_b32 m0, s66
	v_add_u32_e32 v38, s6, v38
	global_load_lds_dwordx4 v36, s[98:99]
	v_lshl_add_u32 v34, v164, 7, v182
	s_mov_b32 m0, s67
	v_max_i32_e32 v164, 0, v38
	global_load_lds_dwordx4 v34, s[100:101]
	v_lshl_add_u32 v36, v164, 7, v180
	s_mov_b32 m0, s48
	v_lshl_add_u32 v34, v164, 7, v182
	global_load_lds_dwordx4 v36, s[98:99]
	s_mov_b32 m0, s49
	v_readlane_b32 s59, v254, 27
	global_load_lds_dwordx4 v34, s[100:101]
	v_add_u32_e32 v34, s6, v38
	v_max_i32_e32 v164, 0, v34
	v_lshl_add_u32 v36, v164, 7, v180
	s_mov_b32 m0, s72
	v_lshl_add_u32 v34, v164, 7, v182
	global_load_lds_dwordx4 v36, s[98:99]
	s_mov_b32 m0, s59
	s_cmp_gt_i32 s58, 32
	global_load_lds_dwordx4 v34, s[100:101]
	ds_read_b128 v[68:71], v225 offset:4096
	ds_read_b128 v[64:67], v226 offset:4096
	s_waitcnt lgkmcnt(0)
	v_mfma_f32_32x32x16_bf16 v[34:49], v[68:71], v[128:131], 0
	ds_read_b128 v[60:63], v227 offset:4096
	ds_read_b128 v[56:59], v228 offset:4096
	ds_read_b64_tr_b16 v[52:53], v229 offset:12288
	ds_read_b64_tr_b16 v[54:55], v229 offset:13312
	ds_read_b64_tr_b16 v[94:95], v229 offset:13376
	ds_read_b64_tr_b16 v[92:93], v229 offset:12352
	ds_read_b64_tr_b16 v[88:89], v229 offset:14336
	ds_read_b64_tr_b16 v[90:91], v229 offset:15360
	ds_read_b64_tr_b16 v[86:87], v229 offset:15424
	ds_read_b64_tr_b16 v[84:85], v229 offset:14400
	v_mfma_f32_32x32x16_bf16 v[34:49], v[64:67], v[124:127], v[34:49]
	s_waitcnt lgkmcnt(9)
	v_mfma_f32_32x32x16_bf16 v[34:49], v[60:63], v[120:123], v[34:49]
	s_waitcnt lgkmcnt(8)
	v_mfma_f32_32x32x16_bf16 v[34:49], v[56:59], v[116:119], v[34:49]
	s_cbranch_scc0 .LBB0_82
	v_sub_u32_e32 v51, v199, v215
	v_mov_b32_e32 v72, v216
	s_nop 0
	s_nop 1
	v_cmp_ge_i32_e32 vcc, 0, v51
	v_cmp_ge_i32_e64 s[24:25], 1, v51
	v_cmp_ge_i32_e64 s[26:27], 2, v51
	v_cmp_ge_i32_e64 s[28:29], 3, v51
	s_nop 1
	v_cndmask_b32_e32 v34, v211, v34, vcc
	v_cmp_ge_i32_e32 vcc, 8, v51
	v_cndmask_b32_e64 v35, v211, v35, s[24:25]
	v_cmp_ge_i32_e64 s[24:25], 9, v51
	v_cndmask_b32_e64 v36, v211, v36, s[26:27]
	v_cmp_ge_i32_e64 s[26:27], 10, v51
	v_cndmask_b32_e64 v37, v211, v37, s[28:29]
	v_cmp_ge_i32_e64 s[28:29], 11, v51
	v_cndmask_b32_e32 v38, v211, v38, vcc
	v_cmp_ge_i32_e32 vcc, 16, v51
	v_cndmask_b32_e64 v39, v211, v39, s[24:25]
	v_cmp_ge_i32_e64 s[24:25], 17, v51
	v_cndmask_b32_e64 v40, v211, v40, s[26:27]
	v_cmp_ge_i32_e64 s[26:27], 18, v51
	v_cndmask_b32_e64 v41, v211, v41, s[28:29]
	v_cmp_ge_i32_e64 s[28:29], 19, v51
	v_cndmask_b32_e32 v42, v211, v42, vcc
	v_cmp_ge_i32_e32 vcc, 24, v51
	v_cndmask_b32_e64 v43, v211, v43, s[24:25]
	v_cmp_ge_i32_e64 s[24:25], 25, v51
	v_cndmask_b32_e64 v44, v211, v44, s[26:27]
	v_cmp_ge_i32_e64 s[26:27], 26, v51
	v_cndmask_b32_e64 v45, v211, v45, s[28:29]
	v_cmp_ge_i32_e64 s[28:29], 27, v51
	v_cndmask_b32_e32 v46, v211, v46, vcc
	v_cndmask_b32_e64 v47, v211, v47, s[24:25]
	v_cndmask_b32_e64 v48, v211, v48, s[26:27]
	v_cndmask_b32_e64 v49, v211, v49, s[28:29]
	s_nop 0
	s_nop 1
; __device__ __forceinline__ unsigned pk2(float lo, float hi) { return pg8::cvt_pk_bf16(lo, hi); }
; __device__ __forceinline__ void att_block(const bf16x8 (&kf)[4], const bf16x8 (&qf)[4], const bf16x8 (&va)[4], f32x16& o0, f32x16& o1, float& mrun, float& lrun, bool domask, int lo_, int hi_) {
;     ...
;     float bmax = -INFINITY;
; #pragma unroll
;     for (int i = 0; i < 16; ++i) bmax = fmaxf(bmax, st[i]);
;     bmax = fmaxf(bmax, __shfl_xor(bmax, 32));
;     const float mnew = fmaxf(mrun, bmax);
;     float lsum = 0.f;
; #pragma unroll
;     for (int i = 0; i < 16; ++i) { st[i] = __builtin_amdgcn_exp2f(st[i] - mnew); lsum += st[i]; }
;     lsum += __shfl_xor(lsum, 32);
;     const float alpha = __builtin_amdgcn_exp2f(mrun - mnew);
;     lrun = lrun * alpha + lsum; mrun = mnew;
; #pragma unroll
;     for (int i = 0; i < 16; ++i) { o0[i] *= alpha; o1[i] *= alpha; }
; #pragma unroll
;     for (int s = 0; s < 2; ++s) { v4u w; w.x = pk2(st[8 * s], st[8 * s + 1]); w.y = pk2(st[8 * s + 2], st[8 * s + 3]); w.z = pk2(st[8 * s + 4], st[8 * s + 5]); w.w = pk2(st[8 * s + 6], st[8 * s + 7]);
;         const bf16x8 pb = __builtin_bit_cast(bf16x8, w);
;         o0 = __builtin_amdgcn_mfma_f32_32x32x16_bf16(va[2 * s], pb, o0, 0, 0, 0);
;         o1 = __builtin_amdgcn_mfma_f32_32x32x16_bf16(va[2 * s + 1], pb, o1, 0, 0, 0); }
; __device__ __forceinline__ void att_phase(unsigned char* ws, LAS unsigned char* lds, int lane, int wave, int G) {
;     ...
;             if (kb >= 1) {
;                 att_block(kf, qfB, va, oB0, oB1, mB, lB, kb == 1 || kb == 5 || kminB > 32 * (kb - 1), mloB - 4 * h - 32 * (kb - 1), qc + 128 - 4 * h - 32 * (kb - 1));
.LBB0_82:
	s_mov_b32 s59, 0xff800000
	s_nop 9
	v_max3_f32 v51, v34, s59, v35
	v_max3_f32 v51, v51, v36, v37
	v_max3_f32 v51, v51, v38, v39
	v_max3_f32 v51, v51, v40, v41
	v_max3_f32 v51, v51, v42, v43
	v_max3_f32 v51, v51, v44, v45
	v_max3_f32 v51, v51, v46, v47
	v_max3_f32 v51, v51, v48, v49
	ds_bpermute_b32 v72, v201, v51
	v_max_i32_e32 v237, s14, v189
	s_mov_b32 s60, 0xff800000
	s_waitcnt lgkmcnt(0)
	v_max3_f32 v148, v50, v51, v72
	v_sub_f32_e32 v34, v34, v148
	v_exp_f32_e32 v72, v34
	v_sub_f32_e32 v35, v35, v148
	v_exp_f32_e32 v73, v35
	v_sub_f32_e32 v35, v36, v148
	v_exp_f32_e32 v74, v35
	v_sub_f32_e32 v35, v37, v148
	v_exp_f32_e32 v75, v35
	v_sub_f32_e32 v35, v38, v148
	v_exp_f32_e32 v76, v35
	v_sub_f32_e32 v35, v39, v148
	v_add_f32_e32 v34, v73, v72
	v_exp_f32_e32 v77, v35
	v_sub_f32_e32 v35, v40, v148
	v_add_f32_e32 v34, v74, v34
	v_exp_f32_e32 v78, v35
	v_sub_f32_e32 v35, v41, v148
	v_add_f32_e32 v34, v75, v34
	v_exp_f32_e32 v79, v35
	v_sub_f32_e32 v35, v42, v148
	v_add_f32_e32 v34, v76, v34
	v_exp_f32_e32 v80, v35
	v_sub_f32_e32 v35, v43, v148
	v_add_f32_e32 v34, v77, v34
	v_exp_f32_e32 v81, v35
	v_sub_f32_e32 v35, v44, v148
	v_add_f32_e32 v34, v78, v34
	v_exp_f32_e32 v82, v35
	v_sub_f32_e32 v35, v45, v148
	v_add_f32_e32 v34, v79, v34
	v_exp_f32_e32 v83, v35
	v_sub_f32_e32 v35, v46, v148
	v_add_f32_e32 v34, v80, v34
	v_exp_f32_e32 v96, v35
	v_sub_f32_e32 v35, v47, v148
	v_add_f32_e32 v34, v81, v34
	v_exp_f32_e32 v97, v35
	v_sub_f32_e32 v35, v48, v148
	v_add_f32_e32 v34, v82, v34
	v_exp_f32_e32 v98, v35
	v_sub_f32_e32 v35, v49, v148
	v_add_f32_e32 v34, v83, v34
	v_exp_f32_e32 v99, v35
	v_add_f32_e32 v34, v96, v34
	v_add_f32_e32 v34, v97, v34
	v_add_f32_e32 v34, v98, v34
	v_add_f32_e32 v235, v99, v34
	v_sub_f32_e32 v34, v50, v148
	v_exp_f32_e32 v188, v34
	ds_bpermute_b32 v236, v201, v235
	v_pk_mul_f32 v[34:35], v[32:33], v[188:189] op_sel_hi:[1,0]
	v_pk_mul_f32 v[32:33], v[30:31], v[188:189] op_sel_hi:[1,0]
	v_pk_mul_f32 v[30:31], v[28:29], v[188:189] op_sel_hi:[1,0]
	v_pk_mul_f32 v[28:29], v[26:27], v[188:189] op_sel_hi:[1,0]
	v_pk_mul_f32 v[26:27], v[24:25], v[188:189] op_sel_hi:[1,0]
	v_pk_mul_f32 v[24:25], v[22:23], v[188:189] op_sel_hi:[1,0]
	v_pk_mul_f32 v[22:23], v[20:21], v[188:189] op_sel_hi:[1,0]
	v_pk_mul_f32 v[20:21], v[18:19], v[188:189] op_sel_hi:[1,0]
	v_pk_mul_f32 v[50:51], v[16:17], v[188:189] op_sel_hi:[1,0]
	v_pk_mul_f32 v[48:49], v[14:15], v[188:189] op_sel_hi:[1,0]
	v_pk_mul_f32 v[46:47], v[12:13], v[188:189] op_sel_hi:[1,0]
	v_pk_mul_f32 v[44:45], v[10:11], v[188:189] op_sel_hi:[1,0]
	v_pk_mul_f32 v[42:43], v[8:9], v[188:189] op_sel_hi:[1,0]
	v_pk_mul_f32 v[40:41], v[6:7], v[188:189] op_sel_hi:[1,0]
	v_pk_mul_f32 v[38:39], v[4:5], v[188:189] op_sel_hi:[1,0]
	v_pk_mul_f32 v[36:37], v[2:3], v[188:189] op_sel_hi:[1,0]
	v_cvt_pk_bf16_f32 v2, v72, v73
	v_cvt_pk_bf16_f32 v3, v74, v75
	v_cvt_pk_bf16_f32 v4, v76, v77
	v_cvt_pk_bf16_f32 v5, v78, v79
	v_sub_u32_e32 v18, v237, v193
	v_mov_b32_e32 v19, v214
	v_mfma_f32_32x32x16_bf16 v[20:35], v[52:55], v[2:5], v[20:35]
	s_waitcnt lgkmcnt(0)
	v_mfma_f32_32x32x16_bf16 v[36:51], v[92:95], v[2:5], v[36:51]
	v_cvt_pk_bf16_f32 v2, v80, v81
	v_cvt_pk_bf16_f32 v3, v82, v83
	v_cvt_pk_bf16_f32 v4, v96, v97
	v_cvt_pk_bf16_f32 v5, v98, v99
	s_nop 1
	v_mfma_f32_32x32x16_bf16 v[20:35], v[88:91], v[2:5], v[20:35]
	v_mfma_f32_32x32x16_bf16 v[36:51], v[84:87], v[2:5], v[36:51]
	v_mfma_f32_32x32x16_bf16 v[2:17], v[68:71], v[112:115], 0
	v_mfma_f32_32x32x16_bf16 v[2:17], v[64:67], v[108:111], v[2:17]
	v_mfma_f32_32x32x16_bf16 v[2:17], v[60:63], v[104:107], v[2:17]
	v_mfma_f32_32x32x16_bf16 v[2:17], v[56:59], v[100:103], v[2:17]
	s_nop 4
	s_cmp_lg_u32 s14, 0
	s_cbranch_scc1 .Lmk_slow_2
	s_mov_b32 vcc_lo, 0x1
	s_mov_b32 vcc_hi, 0x1f
	s_mov_b32 s24, 0x3
	s_mov_b32 s25, 0x3f
	s_mov_b32 s26, 0x7
	s_mov_b32 s27, 0x7f
	s_mov_b32 s28, 0xf
	s_mov_b32 s29, 0xff
	s_nop 2
	v_cndmask_b32_e32 v2, v211, v2, vcc
	s_mov_b32 vcc_lo, 0x1ff
	s_mov_b32 vcc_hi, 0x1fff
	v_cndmask_b32_e64 v3, v211, v3, s[24:25]
	s_mov_b32 s24, 0x3ff
	s_mov_b32 s25, 0x3fff
	v_cndmask_b32_e64 v4, v211, v4, s[26:27]
	s_mov_b32 s26, 0x7ff
	s_mov_b32 s27, 0x7fff
	v_cndmask_b32_e64 v5, v211, v5, s[28:29]
	s_mov_b32 s28, 0xfff
	s_mov_b32 s29, 0xffff
	v_cndmask_b32_e32 v6, v211, v6, vcc
	s_mov_b32 vcc_lo, 0x1ffff
	s_mov_b32 vcc_hi, 0x1fffff
	v_cndmask_b32_e64 v7, v211, v7, s[24:25]
	s_mov_b32 s24, 0x3ffff
	s_mov_b32 s25, 0x3fffff
	v_cndmask_b32_e64 v8, v211, v8, s[26:27]
	s_mov_b32 s26, 0x7ffff
	s_mov_b32 s27, 0x7fffff
	v_cndmask_b32_e64 v9, v211, v9, s[28:29]
	s_mov_b32 s28, 0xfffff
	s_mov_b32 s29, 0xffffff
	v_cndmask_b32_e32 v10, v211, v10, vcc
	s_mov_b32 vcc_lo, 0x1ffffff
	s_mov_b32 vcc_hi, 0x1fffffff
	v_cndmask_b32_e64 v11, v211, v11, s[24:25]
	s_mov_b32 s24, 0x3ffffff
	s_mov_b32 s25, 0x3fffffff
	v_cndmask_b32_e64 v12, v211, v12, s[26:27]
	s_mov_b32 s26, 0x7ffffff
	s_mov_b32 s27, 0x7fffffff
	v_cndmask_b32_e64 v13, v211, v13, s[28:29]
	s_mov_b32 s28, 0xfffffff
	s_mov_b32 s29, 0xffffffff
	v_cndmask_b32_e32 v14, v211, v14, vcc
	v_cndmask_b32_e64 v15, v211, v15, s[24:25]
	v_cndmask_b32_e64 v16, v211, v16, s[26:27]
	v_cndmask_b32_e64 v17, v211, v17, s[28:29]
	s_branch .Lmk_done_2

; #define LAS __attribute__((address_space(3)))
; __device__ __forceinline__ void att_block(const bf16x8 (&kf)[4], const bf16x8 (&qf)[4], const bf16x8 (&va)[4], f32x16& o0, f32x16& o1, float& mrun, float& lrun, bool domask, int lo_, int hi_) {
;     ...
;     float bmax = -INFINITY;
; #pragma unroll
;     for (int i = 0; i < 16; ++i) bmax = fmaxf(bmax, st[i]);
;     bmax = fmaxf(bmax, __shfl_xor(bmax, 32));
;     const float mnew = fmaxf(mrun, bmax);
;     float lsum = 0.f;
; #pragma unroll
;     for (int i = 0; i < 16; ++i) { st[i] = __builtin_amdgcn_exp2f(st[i] - mnew); lsum += st[i]; }
;     lsum += __shfl_xor(lsum, 32);
;     const float alpha = __builtin_amdgcn_exp2f(mrun - mnew);
;     lrun = lrun * alpha + lsum; mrun = mnew;
; #pragma unroll
;     for (int i = 0; i < 16; ++i) { o0[i] *= alpha; o1[i] *= alpha; }
; #pragma unroll
;     for (int s = 0; s < 2; ++s) { v4u w; w.x = pk2(st[8 * s], st[8 * s + 1]); w.y = pk2(st[8 * s + 2], st[8 * s + 3]); w.z = pk2(st[8 * s + 4], st[8 * s + 5]); w.w = pk2(st[8 * s + 6], st[8 * s + 7]);
;         const bf16x8 pb = __builtin_bit_cast(bf16x8, w);
;         o0 = __builtin_amdgcn_mfma_f32_32x32x16_bf16(va[2 * s], pb, o0, 0, 0, 0);
;         o1 = __builtin_amdgcn_mfma_f32_32x32x16_bf16(va[2 * s + 1], pb, o1, 0, 0, 0); }
; __device__ __forceinline__ void att_phase(unsigned char* ws, LAS unsigned char* lds, int lane, int wave, int G) {
;     ...
;             asm volatile("s_waitcnt vmcnt(0)" ::: "memory");
;             if (kb < 5) ATT_DMA_KV(P, kb + 1, sb ^ 1);
;             else if (hn) ATT_DMA_KV(N, 0, sb ^ 1);
;             bf16x8 kf[4], va[4];
; #pragma unroll
;             for (int kk = 0; kk < 4; ++kk) kf[kk] = *(LAS const bf16x8*)(kfb + sb * 4096 + (((2 * kk + h) ^ (qc & 7)) << 4));
;             LAS const unsigned char* trs = trb + 8192 + sb * 4096;
; #pragma unroll
;             for (int s = 0; s < 2; ++s) {
;                 const s16x4 lo0 = vtr(trs + (16 * s) * VP), hi0 = vtr(trs + (16 * s + 8) * VP);
;                 const s16x4 lo1 = vtr(trs + (16 * s) * VP + 64), hi1 = vtr(trs + (16 * s + 8) * VP + 64);
;                 va[2 * s] = (bf16x8){lo0[0], lo0[1], lo0[2], lo0[3], hi0[0], hi0[1], hi0[2], hi0[3]};
;                 va[2 * s + 1] = (bf16x8){lo1[0], lo1[1], lo1[2], lo1[3], hi1[0], hi1[1], hi1[2], hi1[3]};
;             }
;             if (kb <= 4) {
.Lmk_done_2:
	s_nop 0
	v_max3_f32 v18, v2, s59, v3
	v_max3_f32 v18, v18, v4, v5
	v_max3_f32 v18, v18, v6, v7
	v_max3_f32 v18, v18, v8, v9
	v_max3_f32 v18, v18, v10, v11
	v_max3_f32 v18, v18, v12, v13
	v_max3_f32 v18, v18, v14, v15
	v_max3_f32 v18, v18, v16, v17
	ds_bpermute_b32 v19, v201, v18
	s_mov_b32 s59, 0xf149f2ca
	s_waitcnt lgkmcnt(0)
	v_max3_f32 v150, v18, v19, s59
	v_sub_f32_e32 v2, v2, v150
	v_exp_f32_e32 v18, v2
	v_sub_f32_e32 v3, v3, v150
	v_exp_f32_e32 v19, v3
	v_sub_f32_e32 v3, v4, v150
	v_exp_f32_e32 v56, v3
	v_sub_f32_e32 v3, v5, v150
	v_exp_f32_e32 v57, v3
	v_sub_f32_e32 v3, v6, v150
	v_exp_f32_e32 v58, v3
	v_sub_f32_e32 v3, v7, v150
	v_add_f32_e32 v2, v19, v18
	v_exp_f32_e32 v59, v3
	v_sub_f32_e32 v3, v8, v150
	v_add_f32_e32 v2, v56, v2
	v_exp_f32_e32 v60, v3
	v_sub_f32_e32 v3, v9, v150
	v_add_f32_e32 v2, v57, v2
	v_exp_f32_e32 v61, v3
	v_sub_f32_e32 v3, v10, v150
	v_add_f32_e32 v2, v58, v2
	v_exp_f32_e32 v132, v3
	v_sub_f32_e32 v3, v11, v150
	v_add_f32_e32 v2, v59, v2
	v_exp_f32_e32 v133, v3
	v_sub_f32_e32 v3, v12, v150
	v_add_f32_e32 v2, v60, v2
	v_exp_f32_e32 v134, v3
	v_sub_f32_e32 v3, v13, v150
	v_add_f32_e32 v2, v61, v2
	v_exp_f32_e32 v135, v3
	v_sub_f32_e32 v3, v14, v150
	v_add_f32_e32 v2, v132, v2
	v_exp_f32_e32 v136, v3
	v_sub_f32_e32 v3, v15, v150
	v_add_f32_e32 v2, v133, v2
	v_exp_f32_e32 v137, v3
	v_sub_f32_e32 v3, v16, v150
	v_add_f32_e32 v2, v134, v2
	v_exp_f32_e32 v138, v3
	v_sub_f32_e32 v3, v17, v150
	v_add_f32_e32 v2, v135, v2
	v_exp_f32_e32 v139, v3
	v_add_f32_e32 v2, v136, v2
	v_add_f32_e32 v2, v137, v2
	v_add_f32_e32 v2, v138, v2
	v_add_f32_e32 v233, v139, v2
	v_cvt_pk_bf16_f32 v96, v18, v19
	v_cvt_pk_bf16_f32 v97, v56, v57
	v_cvt_pk_bf16_f32 v98, v58, v59
	v_mov_b32_e32 v2, 0
	v_cvt_pk_bf16_f32 v99, v60, v61
	ds_bpermute_b32 v234, v201, v233
	s_nop 0
	v_mfma_f32_32x32x16_bf16 v[68:83], v[52:55], v[96:99], 0
	v_cvt_pk_bf16_f32 v4, v132, v133
	v_cvt_pk_bf16_f32 v5, v134, v135
	v_mfma_f32_32x32x16_bf16 v[52:67], v[92:95], v[96:99], 0
	v_cvt_pk_bf16_f32 v6, v136, v137
	v_cvt_pk_bf16_f32 v7, v138, v139
	s_nop 1
	v_mfma_f32_32x32x16_bf16 v[68:83], v[88:91], v[4:7], v[68:83]
	v_mfma_f32_32x32x16_bf16 v[52:67], v[84:87], v[4:7], v[52:67]
	v_mul_lo_u32 v3, s56, v217
	v_add_u32_e32 v3, s11, v3
	v_max_i32_e32 v164, 0, v3
	s_mov_b32 m0, s57
	s_waitcnt vmcnt(0)
	v_lshl_add_u32 v6, v164, 7, v180
	v_add_u32_e32 v3, s6, v3
	global_load_lds_dwordx4 v6, s[98:99]
	v_lshl_add_u32 v4, v164, 7, v182
	s_mov_b32 m0, s7
	v_max_i32_e32 v164, 0, v3
	global_load_lds_dwordx4 v4, s[100:101]
	v_readlane_b32 s59, v254, 28
	v_lshl_add_u32 v6, v164, 7, v180
	s_mov_b32 m0, s59
	v_readlane_b32 s59, v254, 29
	v_add_u32_e32 v3, s6, v3
	global_load_lds_dwordx4 v6, s[98:99]
	v_lshl_add_u32 v4, v164, 7, v182
	s_mov_b32 m0, s59
	v_max_i32_e32 v164, 0, v3
	global_load_lds_dwordx4 v4, s[100:101]
	v_lshl_add_u32 v6, v164, 7, v180
	s_mov_b32 m0, s15
	v_add_u32_e32 v3, s6, v3
	global_load_lds_dwordx4 v6, s[98:99]
	v_lshl_add_u32 v4, v164, 7, v182
	s_mov_b32 m0, s17
	v_max_i32_e32 v164, 0, v3
	global_load_lds_dwordx4 v4, s[100:101]
	v_lshl_add_u32 v6, v164, 7, v180
	s_mov_b32 m0, s21
	v_readlane_b32 s59, v254, 30
	global_load_lds_dwordx4 v6, s[98:99]
	v_lshl_add_u32 v4, v164, 7, v182
	s_mov_b32 m0, s59
	s_cmpk_lt_i32 s58, 0x41
	global_load_lds_dwordx4 v4, s[100:101]
	ds_read_b128 v[144:147], v225
	ds_read_b128 v[140:143], v226
	s_waitcnt lgkmcnt(0)
	v_mfma_f32_32x32x16_bf16 v[4:19], v[144:147], v[128:131], 0
	ds_read_b128 v[136:139], v227
	ds_read_b128 v[132:135], v228
	ds_read_b64_tr_b16 v[96:97], v229 offset:8192
	ds_read_b64_tr_b16 v[98:99], v229 offset:9216
	ds_read_b64_tr_b16 v[94:95], v229 offset:9280
	ds_read_b64_tr_b16 v[92:93], v229 offset:8256
	ds_read_b64_tr_b16 v[88:89], v229 offset:10240
	ds_read_b64_tr_b16 v[90:91], v229 offset:11264
	ds_read_b64_tr_b16 v[86:87], v229 offset:11328
	ds_read_b64_tr_b16 v[84:85], v229 offset:10304
	v_mfma_f32_32x32x16_bf16 v[4:19], v[140:143], v[124:127], v[4:19]
	s_waitcnt lgkmcnt(9)
	v_mfma_f32_32x32x16_bf16 v[4:19], v[136:139], v[120:123], v[4:19]
	s_waitcnt lgkmcnt(8)
	v_mfma_f32_32x32x16_bf16 v[4:19], v[132:135], v[116:119], v[4:19]
	s_cbranch_scc1 .LBB0_84
	v_sub_u32_e32 v3, v199, v218
	v_mov_b32_e32 v149, v219
	s_nop 0
	s_nop 1
	v_cmp_ge_i32_e32 vcc, 0, v3
	v_cmp_ge_i32_e64 s[24:25], 1, v3
	v_cmp_ge_i32_e64 s[26:27], 2, v3
	v_cmp_ge_i32_e64 s[28:29], 3, v3
	s_nop 1
	v_cndmask_b32_e32 v4, v211, v4, vcc
	v_cmp_ge_i32_e32 vcc, 8, v3
	v_cndmask_b32_e64 v5, v211, v5, s[24:25]
	v_cmp_ge_i32_e64 s[24:25], 9, v3
	v_cndmask_b32_e64 v6, v211, v6, s[26:27]
	v_cmp_ge_i32_e64 s[26:27], 10, v3
	v_cndmask_b32_e64 v7, v211, v7, s[28:29]
	v_cmp_ge_i32_e64 s[28:29], 11, v3
	v_cndmask_b32_e32 v8, v211, v8, vcc
	v_cmp_ge_i32_e32 vcc, 16, v3
	v_cndmask_b32_e64 v9, v211, v9, s[24:25]
	v_cmp_ge_i32_e64 s[24:25], 17, v3
	v_cndmask_b32_e64 v10, v211, v10, s[26:27]
	v_cmp_ge_i32_e64 s[26:27], 18, v3
	v_cndmask_b32_e64 v11, v211, v11, s[28:29]
	v_cmp_ge_i32_e64 s[28:29], 19, v3
	v_cndmask_b32_e32 v12, v211, v12, vcc
	v_cmp_ge_i32_e32 vcc, 24, v3
	v_cndmask_b32_e64 v13, v211, v13, s[24:25]
	v_cmp_ge_i32_e64 s[24:25], 25, v3
	v_cndmask_b32_e64 v14, v211, v14, s[26:27]
	v_cmp_ge_i32_e64 s[26:27], 26, v3
	v_cndmask_b32_e64 v15, v211, v15, s[28:29]
	v_cmp_ge_i32_e64 s[28:29], 27, v3
	v_cndmask_b32_e32 v16, v211, v16, vcc
	v_cndmask_b32_e64 v17, v211, v17, s[24:25]
	v_cndmask_b32_e64 v18, v211, v18, s[26:27]
	v_cndmask_b32_e64 v19, v211, v19, s[28:29]
	s_nop 0
	s_nop 1
; __device__ __forceinline__ unsigned pk2(float lo, float hi) { return pg8::cvt_pk_bf16(lo, hi); }
; __device__ __forceinline__ void att_block(const bf16x8 (&kf)[4], const bf16x8 (&qf)[4], const bf16x8 (&va)[4], f32x16& o0, f32x16& o1, float& mrun, float& lrun, bool domask, int lo_, int hi_) {
;     ...
;     float bmax = -INFINITY;
; #pragma unroll
;     for (int i = 0; i < 16; ++i) bmax = fmaxf(bmax, st[i]);
;     bmax = fmaxf(bmax, __shfl_xor(bmax, 32));
;     const float mnew = fmaxf(mrun, bmax);
;     float lsum = 0.f;
; #pragma unroll
;     for (int i = 0; i < 16; ++i) { st[i] = __builtin_amdgcn_exp2f(st[i] - mnew); lsum += st[i]; }
;     lsum += __shfl_xor(lsum, 32);
;     const float alpha = __builtin_amdgcn_exp2f(mrun - mnew);
;     lrun = lrun * alpha + lsum; mrun = mnew;
; #pragma unroll
;     for (int i = 0; i < 16; ++i) { o0[i] *= alpha; o1[i] *= alpha; }
; #pragma unroll
;     for (int s = 0; s < 2; ++s) { v4u w; w.x = pk2(st[8 * s], st[8 * s + 1]); w.y = pk2(st[8 * s + 2], st[8 * s + 3]); w.z = pk2(st[8 * s + 4], st[8 * s + 5]); w.w = pk2(st[8 * s + 6], st[8 * s + 7]);
;         const bf16x8 pb = __builtin_bit_cast(bf16x8, w);
;         o0 = __builtin_amdgcn_mfma_f32_32x32x16_bf16(va[2 * s], pb, o0, 0, 0, 0);
;         o1 = __builtin_amdgcn_mfma_f32_32x32x16_bf16(va[2 * s + 1], pb, o1, 0, 0, 0); }
; __device__ __forceinline__ void att_phase(unsigned char* ws, LAS unsigned char* lds, int lane, int wave, int G) {
;     ...
;             if (kb >= 1) {
;                 att_block(kf, qfB, va, oB0, oB1, mB, lB, kb == 1 || kb == 5 || kminB > 32 * (kb - 1), mloB - 4 * h - 32 * (kb - 1), qc + 128 - 4 * h - 32 * (kb - 1));
.LBB0_84:
	s_nop 10
	v_max3_f32 v3, v4, s60, v5
	v_max3_f32 v3, v3, v6, v7
	v_max3_f32 v3, v3, v8, v9
	v_max3_f32 v3, v3, v10, v11
	v_max3_f32 v3, v3, v12, v13
	v_max3_f32 v3, v3, v14, v15
	v_max3_f32 v3, v3, v16, v17
	v_max3_f32 v3, v3, v18, v19
	ds_bpermute_b32 v149, v201, v3
	s_cmp_lt_i32 s14, 33
	s_waitcnt lgkmcnt(0)
	v_max3_f32 v149, v148, v3, v149
	v_sub_f32_e32 v3, v4, v149
	v_exp_f32_e32 v3, v3
	v_sub_f32_e32 v5, v5, v149
	v_exp_f32_e32 v151, v5
	v_sub_f32_e32 v5, v6, v149
	v_exp_f32_e32 v152, v5
	v_sub_f32_e32 v5, v7, v149
	v_exp_f32_e32 v153, v5
	v_sub_f32_e32 v5, v8, v149
	v_exp_f32_e32 v154, v5
	v_sub_f32_e32 v5, v9, v149
	v_add_f32_e32 v4, v151, v3
	v_exp_f32_e32 v155, v5
	v_sub_f32_e32 v5, v10, v149
	v_add_f32_e32 v4, v152, v4
	v_exp_f32_e32 v156, v5
	v_sub_f32_e32 v5, v11, v149
	v_add_f32_e32 v4, v153, v4
	v_exp_f32_e32 v157, v5
	v_sub_f32_e32 v5, v12, v149
	v_add_f32_e32 v4, v154, v4
	v_exp_f32_e32 v158, v5
	v_sub_f32_e32 v5, v13, v149
	v_add_f32_e32 v4, v155, v4
	v_exp_f32_e32 v159, v5
	v_sub_f32_e32 v5, v14, v149
	v_add_f32_e32 v4, v156, v4
	v_exp_f32_e32 v160, v5
	v_sub_f32_e32 v5, v15, v149
	v_add_f32_e32 v4, v157, v4
	v_exp_f32_e32 v161, v5
	v_sub_f32_e32 v5, v16, v149
	v_add_f32_e32 v4, v158, v4
	v_exp_f32_e32 v162, v5
	v_sub_f32_e32 v5, v17, v149
	v_add_f32_e32 v4, v159, v4
	v_exp_f32_e32 v163, v5
	v_sub_f32_e32 v5, v18, v149
	v_add_f32_e32 v4, v160, v4
	v_exp_f32_e32 v164, v5
	v_sub_f32_e32 v5, v19, v149
	v_add_f32_e32 v4, v161, v4
	v_exp_f32_e32 v166, v5
	v_add_f32_e32 v4, v162, v4
	v_add_f32_e32 v4, v163, v4
	v_add_f32_e32 v4, v164, v4
	v_add_f32_e32 v239, v166, v4
	v_sub_f32_e32 v4, v148, v149
	v_exp_f32_e32 v192, v4
	ds_bpermute_b32 v240, v201, v239
	v_pk_mul_f32 v[18:19], v[34:35], v[192:193] op_sel_hi:[1,0]
	v_pk_mul_f32 v[16:17], v[32:33], v[192:193] op_sel_hi:[1,0]
	v_pk_mul_f32 v[14:15], v[30:31], v[192:193] op_sel_hi:[1,0]
	v_pk_mul_f32 v[12:13], v[28:29], v[192:193] op_sel_hi:[1,0]
	v_pk_mul_f32 v[10:11], v[26:27], v[192:193] op_sel_hi:[1,0]
	v_pk_mul_f32 v[8:9], v[24:25], v[192:193] op_sel_hi:[1,0]
	v_pk_mul_f32 v[6:7], v[22:23], v[192:193] op_sel_hi:[1,0]
	v_pk_mul_f32 v[4:5], v[20:21], v[192:193] op_sel_hi:[1,0]
	v_pk_mul_f32 v[34:35], v[50:51], v[192:193] op_sel_hi:[1,0]
	v_pk_mul_f32 v[32:33], v[48:49], v[192:193] op_sel_hi:[1,0]
	v_pk_mul_f32 v[30:31], v[46:47], v[192:193] op_sel_hi:[1,0]
	v_pk_mul_f32 v[28:29], v[44:45], v[192:193] op_sel_hi:[1,0]
	v_pk_mul_f32 v[26:27], v[42:43], v[192:193] op_sel_hi:[1,0]
	v_pk_mul_f32 v[24:25], v[40:41], v[192:193] op_sel_hi:[1,0]
	v_pk_mul_f32 v[22:23], v[38:39], v[192:193] op_sel_hi:[1,0]
	v_pk_mul_f32 v[20:21], v[36:37], v[192:193] op_sel_hi:[1,0]
	v_cvt_pk_bf16_f32 v36, v3, v151
	v_cvt_pk_bf16_f32 v37, v152, v153
	v_cvt_pk_bf16_f32 v38, v154, v155
	v_cvt_pk_bf16_f32 v39, v156, v157
	s_nop 1
	v_mfma_f32_32x32x16_bf16 v[4:19], v[96:99], v[36:39], v[4:19]
	v_mfma_f32_32x32x16_bf16 v[20:35], v[92:95], v[36:39], v[20:35]
	v_cvt_pk_bf16_f32 v36, v158, v159
	v_cvt_pk_bf16_f32 v37, v160, v161
	v_cvt_pk_bf16_f32 v38, v162, v163
	v_cvt_pk_bf16_f32 v39, v164, v166
	s_nop 1
	v_mfma_f32_32x32x16_bf16 v[4:19], v[88:91], v[36:39], v[4:19]
	v_mfma_f32_32x32x16_bf16 v[20:35], v[84:87], v[36:39], v[20:35]
	v_mfma_f32_32x32x16_bf16 v[36:51], v[144:147], v[112:115], 0
	v_mfma_f32_32x32x16_bf16 v[36:51], v[140:143], v[108:111], v[36:51]
	v_mfma_f32_32x32x16_bf16 v[36:51], v[136:139], v[104:107], v[36:51]
	v_mfma_f32_32x32x16_bf16 v[36:51], v[132:135], v[100:103], v[36:51]
	s_cbranch_scc1 .LBB0_86
	v_sub_u32_e32 v3, v237, v215
	v_mov_b32_e32 v132, v216
	s_nop 0
	s_nop 1
	v_cmp_ge_i32_e32 vcc, 0, v3
	v_cmp_ge_i32_e64 s[24:25], 1, v3
	v_cmp_ge_i32_e64 s[26:27], 2, v3
	v_cmp_ge_i32_e64 s[28:29], 3, v3
	s_nop 1
	v_cndmask_b32_e32 v36, v211, v36, vcc
	v_cmp_ge_i32_e32 vcc, 8, v3
	v_cndmask_b32_e64 v37, v211, v37, s[24:25]
	v_cmp_ge_i32_e64 s[24:25], 9, v3
	v_cndmask_b32_e64 v38, v211, v38, s[26:27]
	v_cmp_ge_i32_e64 s[26:27], 10, v3
	v_cndmask_b32_e64 v39, v211, v39, s[28:29]
	v_cmp_ge_i32_e64 s[28:29], 11, v3
	v_cndmask_b32_e32 v40, v211, v40, vcc
	v_cmp_ge_i32_e32 vcc, 16, v3
	v_cndmask_b32_e64 v41, v211, v41, s[24:25]
	v_cmp_ge_i32_e64 s[24:25], 17, v3
	v_cndmask_b32_e64 v42, v211, v42, s[26:27]
	v_cmp_ge_i32_e64 s[26:27], 18, v3
	v_cndmask_b32_e64 v43, v211, v43, s[28:29]
	v_cmp_ge_i32_e64 s[28:29], 19, v3
	v_cndmask_b32_e32 v44, v211, v44, vcc
	v_cmp_ge_i32_e32 vcc, 24, v3
	v_cndmask_b32_e64 v45, v211, v45, s[24:25]
	v_cmp_ge_i32_e64 s[24:25], 25, v3
	v_cndmask_b32_e64 v46, v211, v46, s[26:27]
	v_cmp_ge_i32_e64 s[26:27], 26, v3
	v_cndmask_b32_e64 v47, v211, v47, s[28:29]
	v_cmp_ge_i32_e64 s[28:29], 27, v3
	v_cndmask_b32_e32 v48, v211, v48, vcc
	v_cndmask_b32_e64 v49, v211, v49, s[24:25]
	v_cndmask_b32_e64 v50, v211, v50, s[26:27]
	v_cndmask_b32_e64 v51, v211, v51, s[28:29]
	s_nop 0
	s_nop 1
; #define LAS __attribute__((address_space(3)))
; __device__ __forceinline__ void att_block(const bf16x8 (&kf)[4], const bf16x8 (&qf)[4], const bf16x8 (&va)[4], f32x16& o0, f32x16& o1, float& mrun, float& lrun, bool domask, int lo_, int hi_) {
;     ...
;     float bmax = -INFINITY;
; #pragma unroll
;     for (int i = 0; i < 16; ++i) bmax = fmaxf(bmax, st[i]);
;     bmax = fmaxf(bmax, __shfl_xor(bmax, 32));
;     const float mnew = fmaxf(mrun, bmax);
;     float lsum = 0.f;
; #pragma unroll
;     for (int i = 0; i < 16; ++i) { st[i] = __builtin_amdgcn_exp2f(st[i] - mnew); lsum += st[i]; }
;     lsum += __shfl_xor(lsum, 32);
;     const float alpha = __builtin_amdgcn_exp2f(mrun - mnew);
;     lrun = lrun * alpha + lsum; mrun = mnew;
; #pragma unroll
;     for (int i = 0; i < 16; ++i) { o0[i] *= alpha; o1[i] *= alpha; }
; #pragma unroll
;     for (int s = 0; s < 2; ++s) { v4u w; w.x = pk2(st[8 * s], st[8 * s + 1]); w.y = pk2(st[8 * s + 2], st[8 * s + 3]); w.z = pk2(st[8 * s + 4], st[8 * s + 5]); w.w = pk2(st[8 * s + 6], st[8 * s + 7]);
;         const bf16x8 pb = __builtin_bit_cast(bf16x8, w);
;         o0 = __builtin_amdgcn_mfma_f32_32x32x16_bf16(va[2 * s], pb, o0, 0, 0, 0);
;         o1 = __builtin_amdgcn_mfma_f32_32x32x16_bf16(va[2 * s + 1], pb, o1, 0, 0, 0); }
; __device__ __forceinline__ void att_phase(unsigned char* ws, LAS unsigned char* lds, int lane, int wave, int G) {
;     ...
;             asm volatile("s_waitcnt vmcnt(0)" ::: "memory");
;             if (kb < 5) ATT_DMA_KV(P, kb + 1, sb ^ 1);
;             else if (hn) ATT_DMA_KV(N, 0, sb ^ 1);
;             bf16x8 kf[4], va[4];
; #pragma unroll
;             for (int kk = 0; kk < 4; ++kk) kf[kk] = *(LAS const bf16x8*)(kfb + sb * 4096 + (((2 * kk + h) ^ (qc & 7)) << 4));
;             LAS const unsigned char* trs = trb + 8192 + sb * 4096;
; #pragma unroll
;             for (int s = 0; s < 2; ++s) {
;                 const s16x4 lo0 = vtr(trs + (16 * s) * VP), hi0 = vtr(trs + (16 * s + 8) * VP);
;                 const s16x4 lo1 = vtr(trs + (16 * s) * VP + 64), hi1 = vtr(trs + (16 * s + 8) * VP + 64);
;                 va[2 * s] = (bf16x8){lo0[0], lo0[1], lo0[2], lo0[3], hi0[0], hi0[1], hi0[2], hi0[3]};
;                 va[2 * s + 1] = (bf16x8){lo1[0], lo1[1], lo1[2], lo1[3], hi1[0], hi1[1], hi1[2], hi1[3]};
;             }
;             if (kb <= 4) {
.LBB0_86:
	s_nop 10
	v_max3_f32 v3, v36, s60, v37
	v_max3_f32 v3, v3, v38, v39
	v_max3_f32 v3, v3, v40, v41
	v_max3_f32 v3, v3, v42, v43
	v_max3_f32 v3, v3, v44, v45
	v_max3_f32 v3, v3, v46, v47
	v_max3_f32 v3, v3, v48, v49
	v_max3_f32 v3, v3, v50, v51
	ds_bpermute_b32 v132, v201, v3
	s_waitcnt lgkmcnt(0)
	s_waitcnt lgkmcnt(0)
	v_max3_f32 v148, v150, v3, v132
	v_sub_f32_e32 v3, v36, v148
	v_sub_f32_e32 v36, v37, v148
	v_exp_f32_e32 v133, v36
	v_sub_f32_e32 v36, v38, v148
	v_exp_f32_e32 v134, v36
	v_sub_f32_e32 v36, v39, v148
	v_exp_f32_e32 v135, v36
	v_sub_f32_e32 v36, v40, v148
	v_exp_f32_e32 v136, v36
	v_sub_f32_e32 v36, v41, v148
	v_exp_f32_e32 v137, v36
	v_sub_f32_e32 v36, v42, v148
	v_exp_f32_e32 v138, v36
	v_sub_f32_e32 v36, v43, v148
	v_exp_f32_e32 v139, v36
	v_sub_f32_e32 v36, v44, v148
	v_exp_f32_e32 v140, v36
	v_sub_f32_e32 v36, v45, v148
	v_exp_f32_e32 v141, v36
	v_sub_f32_e32 v36, v46, v148
	v_exp_f32_e32 v142, v36
	v_sub_f32_e32 v36, v47, v148
	v_exp_f32_e32 v143, v36
	v_sub_f32_e32 v36, v48, v148
	v_exp_f32_e32 v132, v3
	v_exp_f32_e32 v144, v36
	v_sub_f32_e32 v36, v49, v148
	v_exp_f32_e32 v145, v36
	v_sub_f32_e32 v36, v50, v148
	v_exp_f32_e32 v146, v36
	v_sub_f32_e32 v36, v51, v148
	v_exp_f32_e32 v147, v36
	v_sub_f32_e32 v36, v150, v148
	v_exp_f32_e32 v190, v36
	v_add_f32_e32 v3, v133, v132
	v_add_f32_e32 v3, v134, v3
	v_add_f32_e32 v3, v135, v3
	v_add_f32_e32 v3, v136, v3
	v_pk_mul_f32 v[50:51], v[82:83], v[190:191] op_sel_hi:[1,0]
	v_pk_mul_f32 v[48:49], v[80:81], v[190:191] op_sel_hi:[1,0]
	v_pk_mul_f32 v[46:47], v[78:79], v[190:191] op_sel_hi:[1,0]
	v_pk_mul_f32 v[44:45], v[76:77], v[190:191] op_sel_hi:[1,0]
	v_pk_mul_f32 v[42:43], v[74:75], v[190:191] op_sel_hi:[1,0]
	v_pk_mul_f32 v[40:41], v[72:73], v[190:191] op_sel_hi:[1,0]
	v_pk_mul_f32 v[38:39], v[70:71], v[190:191] op_sel_hi:[1,0]
	v_pk_mul_f32 v[36:37], v[68:69], v[190:191] op_sel_hi:[1,0]
	v_pk_mul_f32 v[66:67], v[66:67], v[190:191] op_sel_hi:[1,0]
	v_pk_mul_f32 v[64:65], v[64:65], v[190:191] op_sel_hi:[1,0]
	v_pk_mul_f32 v[62:63], v[62:63], v[190:191] op_sel_hi:[1,0]
	v_pk_mul_f32 v[60:61], v[60:61], v[190:191] op_sel_hi:[1,0]
	v_pk_mul_f32 v[58:59], v[58:59], v[190:191] op_sel_hi:[1,0]
	v_pk_mul_f32 v[56:57], v[56:57], v[190:191] op_sel_hi:[1,0]
	v_pk_mul_f32 v[54:55], v[54:55], v[190:191] op_sel_hi:[1,0]
	v_pk_mul_f32 v[52:53], v[52:53], v[190:191] op_sel_hi:[1,0]
	v_cvt_pk_bf16_f32 v68, v132, v133
	v_cvt_pk_bf16_f32 v69, v134, v135
	v_cvt_pk_bf16_f32 v70, v136, v137
	v_cvt_pk_bf16_f32 v71, v138, v139
	v_add_f32_e32 v3, v137, v3
	v_add_f32_e32 v3, v138, v3
	v_mfma_f32_32x32x16_bf16 v[36:51], v[96:99], v[68:71], v[36:51]
	v_add_f32_e32 v3, v139, v3
	v_add_f32_e32 v3, v140, v3
	v_add_f32_e32 v3, v141, v3
	v_add_f32_e32 v3, v142, v3
	v_add_f32_e32 v3, v143, v3
	v_add_f32_e32 v3, v144, v3
	v_add_f32_e32 v3, v145, v3
	v_mfma_f32_32x32x16_bf16 v[52:67], v[92:95], v[68:71], v[52:67]
	v_cvt_pk_bf16_f32 v68, v140, v141
	v_cvt_pk_bf16_f32 v69, v142, v143
	v_cvt_pk_bf16_f32 v70, v144, v145
	v_cvt_pk_bf16_f32 v71, v146, v147
	v_add_f32_e32 v3, v146, v3
	v_add_f32_e32 v3, v147, v3
	ds_bpermute_b32 v238, v201, v3
	v_mfma_f32_32x32x16_bf16 v[36:51], v[88:91], v[68:71], v[36:51]
	v_mfma_f32_32x32x16_bf16 v[52:67], v[84:87], v[68:71], v[52:67]
	v_mul_lo_u32 v68, s56, v191
	v_add_u32_e32 v72, s11, v68
	v_max_i32_e32 v164, 0, v72
	s_mov_b32 m0, s33
	s_waitcnt vmcnt(0)
	v_lshl_add_u32 v70, v164, 7, v180
	v_add_u32_e32 v72, s6, v72
	global_load_lds_dwordx4 v70, s[98:99]
	v_lshl_add_u32 v68, v164, 7, v182
	s_mov_b32 m0, s44
	v_max_i32_e32 v164, 0, v72
	global_load_lds_dwordx4 v68, s[100:101]
	v_lshl_add_u32 v70, v164, 7, v180
	s_mov_b32 m0, s66
	v_add_u32_e32 v72, s6, v72
	global_load_lds_dwordx4 v70, s[98:99]
	v_lshl_add_u32 v68, v164, 7, v182
	s_mov_b32 m0, s67
	v_max_i32_e32 v164, 0, v72
	global_load_lds_dwordx4 v68, s[100:101]
	v_lshl_add_u32 v70, v164, 7, v180
	s_mov_b32 m0, s48
	v_lshl_add_u32 v68, v164, 7, v182
	global_load_lds_dwordx4 v70, s[98:99]
	s_mov_b32 m0, s49
	v_readlane_b32 s59, v254, 27
	global_load_lds_dwordx4 v68, s[100:101]
	v_add_u32_e32 v68, s6, v72
	v_max_i32_e32 v164, 0, v68
	v_lshl_add_u32 v70, v164, 7, v180
	s_mov_b32 m0, s72
	v_lshl_add_u32 v68, v164, 7, v182
	global_load_lds_dwordx4 v70, s[98:99]
	s_mov_b32 m0, s59
	s_cmpk_lt_i32 s58, 0x61
	global_load_lds_dwordx4 v68, s[100:101]
	ds_read_b128 v[96:99], v225 offset:4096
	ds_read_b128 v[92:95], v226 offset:4096
	s_waitcnt lgkmcnt(0)
	v_mfma_f32_32x32x16_bf16 v[68:83], v[96:99], v[128:131], 0
	ds_read_b128 v[88:91], v227 offset:4096
	ds_read_b128 v[84:87], v228 offset:4096
	ds_read_b64_tr_b16 v[144:145], v229 offset:12288
	ds_read_b64_tr_b16 v[146:147], v229 offset:13312
	ds_read_b64_tr_b16 v[142:143], v229 offset:13376
	ds_read_b64_tr_b16 v[140:141], v229 offset:12352
	ds_read_b64_tr_b16 v[136:137], v229 offset:14336
	ds_read_b64_tr_b16 v[138:139], v229 offset:15360
	ds_read_b64_tr_b16 v[134:135], v229 offset:15424
	ds_read_b64_tr_b16 v[132:133], v229 offset:14400
	v_mfma_f32_32x32x16_bf16 v[68:83], v[92:95], v[124:127], v[68:83]
	s_waitcnt lgkmcnt(9)
	v_mfma_f32_32x32x16_bf16 v[68:83], v[88:91], v[120:123], v[68:83]
	s_waitcnt lgkmcnt(8)
	v_mfma_f32_32x32x16_bf16 v[68:83], v[84:87], v[116:119], v[68:83]
	s_cbranch_scc1 .LBB0_88
	v_sub_u32_e32 v150, v199, v220
	v_mov_b32_e32 v151, v221
	s_nop 0
	s_nop 1
	v_cmp_ge_i32_e32 vcc, 0, v150
	v_cmp_ge_i32_e64 s[24:25], 1, v150
	v_cmp_ge_i32_e64 s[26:27], 2, v150
	v_cmp_ge_i32_e64 s[28:29], 3, v150
	s_nop 1
	v_cndmask_b32_e32 v68, v211, v68, vcc
	v_cmp_ge_i32_e32 vcc, 8, v150
	v_cndmask_b32_e64 v69, v211, v69, s[24:25]
	v_cmp_ge_i32_e64 s[24:25], 9, v150
	v_cndmask_b32_e64 v70, v211, v70, s[26:27]
	v_cmp_ge_i32_e64 s[26:27], 10, v150
	v_cndmask_b32_e64 v71, v211, v71, s[28:29]
	v_cmp_ge_i32_e64 s[28:29], 11, v150
	v_cndmask_b32_e32 v72, v211, v72, vcc
	v_cmp_ge_i32_e32 vcc, 16, v150
	v_cndmask_b32_e64 v73, v211, v73, s[24:25]
	v_cmp_ge_i32_e64 s[24:25], 17, v150
	v_cndmask_b32_e64 v74, v211, v74, s[26:27]
	v_cmp_ge_i32_e64 s[26:27], 18, v150
	v_cndmask_b32_e64 v75, v211, v75, s[28:29]
	v_cmp_ge_i32_e64 s[28:29], 19, v150
	v_cndmask_b32_e32 v76, v211, v76, vcc
	v_cmp_ge_i32_e32 vcc, 24, v150
	v_cndmask_b32_e64 v77, v211, v77, s[24:25]
	v_cmp_ge_i32_e64 s[24:25], 25, v150
	v_cndmask_b32_e64 v78, v211, v78, s[26:27]
	v_cmp_ge_i32_e64 s[26:27], 26, v150
	v_cndmask_b32_e64 v79, v211, v79, s[28:29]
	v_cmp_ge_i32_e64 s[28:29], 27, v150
	v_cndmask_b32_e32 v80, v211, v80, vcc
	v_cndmask_b32_e64 v81, v211, v81, s[24:25]
	v_cndmask_b32_e64 v82, v211, v82, s[26:27]
	v_cndmask_b32_e64 v83, v211, v83, s[28:29]
	s_nop 0
	s_nop 1
; __device__ __forceinline__ unsigned pk2(float lo, float hi) { return pg8::cvt_pk_bf16(lo, hi); }
; __device__ __forceinline__ void att_block(const bf16x8 (&kf)[4], const bf16x8 (&qf)[4], const bf16x8 (&va)[4], f32x16& o0, f32x16& o1, float& mrun, float& lrun, bool domask, int lo_, int hi_) {
;     ...
;     float bmax = -INFINITY;
; #pragma unroll
;     for (int i = 0; i < 16; ++i) bmax = fmaxf(bmax, st[i]);
;     bmax = fmaxf(bmax, __shfl_xor(bmax, 32));
;     const float mnew = fmaxf(mrun, bmax);
;     float lsum = 0.f;
; #pragma unroll
;     for (int i = 0; i < 16; ++i) { st[i] = __builtin_amdgcn_exp2f(st[i] - mnew); lsum += st[i]; }
;     lsum += __shfl_xor(lsum, 32);
;     const float alpha = __builtin_amdgcn_exp2f(mrun - mnew);
;     lrun = lrun * alpha + lsum; mrun = mnew;
; #pragma unroll
;     for (int i = 0; i < 16; ++i) { o0[i] *= alpha; o1[i] *= alpha; }
; #pragma unroll
;     for (int s = 0; s < 2; ++s) { v4u w; w.x = pk2(st[8 * s], st[8 * s + 1]); w.y = pk2(st[8 * s + 2], st[8 * s + 3]); w.z = pk2(st[8 * s + 4], st[8 * s + 5]); w.w = pk2(st[8 * s + 6], st[8 * s + 7]);
;         const bf16x8 pb = __builtin_bit_cast(bf16x8, w);
;         o0 = __builtin_amdgcn_mfma_f32_32x32x16_bf16(va[2 * s], pb, o0, 0, 0, 0);
;         o1 = __builtin_amdgcn_mfma_f32_32x32x16_bf16(va[2 * s + 1], pb, o1, 0, 0, 0); }
; __device__ __forceinline__ void att_phase(unsigned char* ws, LAS unsigned char* lds, int lane, int wave, int G) {
;     ...
;             if (kb >= 1) {
;                 att_block(kf, qfB, va, oB0, oB1, mB, lB, kb == 1 || kb == 5 || kminB > 32 * (kb - 1), mloB - 4 * h - 32 * (kb - 1), qc + 128 - 4 * h - 32 * (kb - 1));
.LBB0_88:
	s_nop 10
	v_max3_f32 v150, v68, s60, v69
	v_max3_f32 v150, v150, v70, v71
	v_max3_f32 v150, v150, v72, v73
	v_max3_f32 v150, v150, v74, v75
	v_max3_f32 v150, v150, v76, v77
	v_max3_f32 v150, v150, v78, v79
	v_max3_f32 v150, v150, v80, v81
	v_max3_f32 v150, v150, v82, v83
	ds_bpermute_b32 v151, v201, v150
	s_cmpk_lt_i32 s14, 0x41
	s_waitcnt lgkmcnt(0)
	v_max3_f32 v202, v149, v150, v151
	v_sub_f32_e32 v68, v68, v202
	v_exp_f32_e32 v68, v68
	v_sub_f32_e32 v69, v69, v202
	v_exp_f32_e32 v69, v69
	v_sub_f32_e32 v70, v70, v202
	v_exp_f32_e32 v70, v70
	v_sub_f32_e32 v71, v71, v202
	v_exp_f32_e32 v71, v71
	v_sub_f32_e32 v72, v72, v202
	v_exp_f32_e32 v72, v72
	v_sub_f32_e32 v73, v73, v202
	v_add_f32_e32 v150, v69, v68
	v_exp_f32_e32 v73, v73
	v_sub_f32_e32 v74, v74, v202
	v_sub_f32_e32 v75, v75, v202
	v_sub_f32_e32 v149, v149, v202
	v_add_f32_e32 v150, v70, v150
	v_exp_f32_e32 v74, v74
	v_exp_f32_e32 v75, v75
	v_exp_f32_e32 v196, v149
	v_add_f32_e32 v150, v71, v150
	v_sub_f32_e32 v76, v76, v202
	v_add_f32_e32 v150, v72, v150
	v_exp_f32_e32 v76, v76
	v_sub_f32_e32 v77, v77, v202
	v_add_f32_e32 v150, v73, v150
	v_exp_f32_e32 v77, v77
	v_sub_f32_e32 v78, v78, v202
	v_add_f32_e32 v150, v74, v150
	v_exp_f32_e32 v78, v78
	v_sub_f32_e32 v79, v79, v202
	v_pk_mul_f32 v[18:19], v[18:19], v[196:197] op_sel_hi:[1,0]
	v_pk_mul_f32 v[16:17], v[16:17], v[196:197] op_sel_hi:[1,0]
	v_pk_mul_f32 v[14:15], v[14:15], v[196:197] op_sel_hi:[1,0]
	v_pk_mul_f32 v[12:13], v[12:13], v[196:197] op_sel_hi:[1,0]
	v_pk_mul_f32 v[10:11], v[10:11], v[196:197] op_sel_hi:[1,0]
	v_pk_mul_f32 v[8:9], v[8:9], v[196:197] op_sel_hi:[1,0]
	v_pk_mul_f32 v[6:7], v[6:7], v[196:197] op_sel_hi:[1,0]
	v_pk_mul_f32 v[4:5], v[4:5], v[196:197] op_sel_hi:[1,0]
	v_pk_mul_f32 v[34:35], v[34:35], v[196:197] op_sel_hi:[1,0]
	v_pk_mul_f32 v[32:33], v[32:33], v[196:197] op_sel_hi:[1,0]
	v_pk_mul_f32 v[30:31], v[30:31], v[196:197] op_sel_hi:[1,0]
	v_pk_mul_f32 v[28:29], v[28:29], v[196:197] op_sel_hi:[1,0]
	v_pk_mul_f32 v[26:27], v[26:27], v[196:197] op_sel_hi:[1,0]
	v_pk_mul_f32 v[24:25], v[24:25], v[196:197] op_sel_hi:[1,0]
	v_pk_mul_f32 v[22:23], v[22:23], v[196:197] op_sel_hi:[1,0]
	v_pk_mul_f32 v[20:21], v[20:21], v[196:197] op_sel_hi:[1,0]
	v_cvt_pk_bf16_f32 v68, v68, v69
	v_cvt_pk_bf16_f32 v69, v70, v71
	v_cvt_pk_bf16_f32 v70, v72, v73
	v_cvt_pk_bf16_f32 v71, v74, v75
	v_add_f32_e32 v150, v75, v150
	v_exp_f32_e32 v79, v79
	v_sub_f32_e32 v80, v80, v202
	v_mfma_f32_32x32x16_bf16 v[4:19], v[144:147], v[68:71], v[4:19]
	v_add_f32_e32 v150, v76, v150
	v_exp_f32_e32 v80, v80
	v_sub_f32_e32 v81, v81, v202
	v_add_f32_e32 v150, v77, v150
	v_exp_f32_e32 v81, v81
	v_sub_f32_e32 v82, v82, v202
	v_sub_f32_e32 v83, v83, v202
	v_mfma_f32_32x32x16_bf16 v[20:35], v[140:143], v[68:71], v[20:35]
	v_add_f32_e32 v150, v78, v150
	v_exp_f32_e32 v82, v82
	v_exp_f32_e32 v83, v83
	v_add_f32_e32 v150, v79, v150
	v_add_f32_e32 v150, v80, v150
	v_add_f32_e32 v150, v81, v150
	v_add_f32_e32 v150, v82, v150
	v_cvt_pk_bf16_f32 v68, v76, v77
	v_cvt_pk_bf16_f32 v69, v78, v79
	v_cvt_pk_bf16_f32 v70, v80, v81
	v_cvt_pk_bf16_f32 v71, v82, v83
	v_add_f32_e32 v243, v83, v150
	ds_bpermute_b32 v244, v201, v243
	v_mfma_f32_32x32x16_bf16 v[4:19], v[136:139], v[68:71], v[4:19]
	v_mfma_f32_32x32x16_bf16 v[20:35], v[132:135], v[68:71], v[20:35]
	v_mfma_f32_32x32x16_bf16 v[68:83], v[96:99], v[112:115], 0
	v_mfma_f32_32x32x16_bf16 v[68:83], v[92:95], v[108:111], v[68:83]
	v_mfma_f32_32x32x16_bf16 v[68:83], v[88:91], v[104:107], v[68:83]
	v_mfma_f32_32x32x16_bf16 v[68:83], v[84:87], v[100:103], v[68:83]
	s_cbranch_scc1 .LBB0_90
	v_sub_u32_e32 v84, v237, v218
	v_mov_b32_e32 v85, v219
	s_nop 0
	s_nop 1
	v_cmp_ge_i32_e32 vcc, 0, v84
	v_cmp_ge_i32_e64 s[24:25], 1, v84
	v_cmp_ge_i32_e64 s[26:27], 2, v84
	v_cmp_ge_i32_e64 s[28:29], 3, v84
	s_nop 1
	v_cndmask_b32_e32 v68, v211, v68, vcc
	v_cmp_ge_i32_e32 vcc, 8, v84
	v_cndmask_b32_e64 v69, v211, v69, s[24:25]
	v_cmp_ge_i32_e64 s[24:25], 9, v84
	v_cndmask_b32_e64 v70, v211, v70, s[26:27]
	v_cmp_ge_i32_e64 s[26:27], 10, v84
	v_cndmask_b32_e64 v71, v211, v71, s[28:29]
	v_cmp_ge_i32_e64 s[28:29], 11, v84
	v_cndmask_b32_e32 v72, v211, v72, vcc
	v_cmp_ge_i32_e32 vcc, 16, v84
	v_cndmask_b32_e64 v73, v211, v73, s[24:25]
	v_cmp_ge_i32_e64 s[24:25], 17, v84
	v_cndmask_b32_e64 v74, v211, v74, s[26:27]
	v_cmp_ge_i32_e64 s[26:27], 18, v84
	v_cndmask_b32_e64 v75, v211, v75, s[28:29]
	v_cmp_ge_i32_e64 s[28:29], 19, v84
	v_cndmask_b32_e32 v76, v211, v76, vcc
	v_cmp_ge_i32_e32 vcc, 24, v84
	v_cndmask_b32_e64 v77, v211, v77, s[24:25]
	v_cmp_ge_i32_e64 s[24:25], 25, v84
	v_cndmask_b32_e64 v78, v211, v78, s[26:27]
	v_cmp_ge_i32_e64 s[26:27], 26, v84
	v_cndmask_b32_e64 v79, v211, v79, s[28:29]
	v_cmp_ge_i32_e64 s[28:29], 27, v84
	v_cndmask_b32_e32 v80, v211, v80, vcc
	v_cndmask_b32_e64 v81, v211, v81, s[24:25]
	v_cndmask_b32_e64 v82, v211, v82, s[26:27]
	v_cndmask_b32_e64 v83, v211, v83, s[28:29]
	s_nop 0
	s_nop 1
; #define LAS __attribute__((address_space(3)))
; __device__ __forceinline__ void att_block(const bf16x8 (&kf)[4], const bf16x8 (&qf)[4], const bf16x8 (&va)[4], f32x16& o0, f32x16& o1, float& mrun, float& lrun, bool domask, int lo_, int hi_) {
;     ...
;     float bmax = -INFINITY;
; #pragma unroll
;     for (int i = 0; i < 16; ++i) bmax = fmaxf(bmax, st[i]);
;     bmax = fmaxf(bmax, __shfl_xor(bmax, 32));
;     const float mnew = fmaxf(mrun, bmax);
;     float lsum = 0.f;
; #pragma unroll
;     for (int i = 0; i < 16; ++i) { st[i] = __builtin_amdgcn_exp2f(st[i] - mnew); lsum += st[i]; }
;     lsum += __shfl_xor(lsum, 32);
;     const float alpha = __builtin_amdgcn_exp2f(mrun - mnew);
;     lrun = lrun * alpha + lsum; mrun = mnew;
; #pragma unroll
;     for (int i = 0; i < 16; ++i) { o0[i] *= alpha; o1[i] *= alpha; }
; #pragma unroll
;     for (int s = 0; s < 2; ++s) { v4u w; w.x = pk2(st[8 * s], st[8 * s + 1]); w.y = pk2(st[8 * s + 2], st[8 * s + 3]); w.z = pk2(st[8 * s + 4], st[8 * s + 5]); w.w = pk2(st[8 * s + 6], st[8 * s + 7]);
;         const bf16x8 pb = __builtin_bit_cast(bf16x8, w);
;         o0 = __builtin_amdgcn_mfma_f32_32x32x16_bf16(va[2 * s], pb, o0, 0, 0, 0);
;         o1 = __builtin_amdgcn_mfma_f32_32x32x16_bf16(va[2 * s + 1], pb, o1, 0, 0, 0); }
; __device__ __forceinline__ void att_phase(unsigned char* ws, LAS unsigned char* lds, int lane, int wave, int G) {
;     ...
;             asm volatile("s_waitcnt vmcnt(0)" ::: "memory");
;             if (kb < 5) ATT_DMA_KV(P, kb + 1, sb ^ 1);
;             else if (hn) ATT_DMA_KV(N, 0, sb ^ 1);
;             bf16x8 kf[4], va[4];
; #pragma unroll
;             for (int kk = 0; kk < 4; ++kk) kf[kk] = *(LAS const bf16x8*)(kfb + sb * 4096 + (((2 * kk + h) ^ (qc & 7)) << 4));
;             LAS const unsigned char* trs = trb + 8192 + sb * 4096;
; #pragma unroll
;             for (int s = 0; s < 2; ++s) {
;                 const s16x4 lo0 = vtr(trs + (16 * s) * VP), hi0 = vtr(trs + (16 * s + 8) * VP);
;                 const s16x4 lo1 = vtr(trs + (16 * s) * VP + 64), hi1 = vtr(trs + (16 * s + 8) * VP + 64);
;                 va[2 * s] = (bf16x8){lo0[0], lo0[1], lo0[2], lo0[3], hi0[0], hi0[1], hi0[2], hi0[3]};
;                 va[2 * s + 1] = (bf16x8){lo1[0], lo1[1], lo1[2], lo1[3], hi1[0], hi1[1], hi1[2], hi1[3]};
;             }
.LBB0_90:
	v_mul_lo_u32 v84, s52, v189
	s_mov_b32 s58, 0xff800000
	v_add_u32_e32 v198, s53, v84
	s_nop 7
	v_max3_f32 v84, v68, s58, v69
	v_max3_f32 v84, v84, v70, v71
	v_max3_f32 v84, v84, v72, v73
	v_max3_f32 v84, v84, v74, v75
	v_max3_f32 v84, v84, v76, v77
	v_max3_f32 v84, v84, v78, v79
	v_max3_f32 v84, v84, v80, v81
	v_max3_f32 v84, v84, v82, v83
	ds_bpermute_b32 v85, v201, v84
	s_waitcnt lgkmcnt(0)
	s_waitcnt lgkmcnt(0)
	v_max3_f32 v245, v148, v84, v85
	v_sub_f32_e32 v68, v68, v245
	v_exp_f32_e32 v149, v68
	v_sub_f32_e32 v69, v69, v245
	v_exp_f32_e32 v150, v69
	v_sub_f32_e32 v69, v70, v245
	v_exp_f32_e32 v151, v69
	v_sub_f32_e32 v69, v71, v245
	v_exp_f32_e32 v152, v69
	v_sub_f32_e32 v69, v72, v245
	v_exp_f32_e32 v153, v69
	v_sub_f32_e32 v69, v73, v245
	v_add_f32_e32 v68, v150, v149
	v_exp_f32_e32 v154, v69
	v_sub_f32_e32 v69, v74, v245
	v_add_f32_e32 v68, v151, v68
	v_exp_f32_e32 v155, v69
	v_sub_f32_e32 v69, v75, v245
	v_add_f32_e32 v68, v152, v68
	v_exp_f32_e32 v156, v69
	v_sub_f32_e32 v69, v76, v245
	v_add_f32_e32 v68, v153, v68
	v_exp_f32_e32 v157, v69
	v_sub_f32_e32 v69, v77, v245
	v_add_f32_e32 v68, v154, v68
	v_exp_f32_e32 v158, v69
	v_sub_f32_e32 v69, v78, v245
	v_add_f32_e32 v68, v155, v68
	v_exp_f32_e32 v159, v69
	v_sub_f32_e32 v69, v79, v245
	v_add_f32_e32 v68, v156, v68
	v_exp_f32_e32 v160, v69
	v_sub_f32_e32 v69, v80, v245
	v_add_f32_e32 v68, v157, v68
	v_exp_f32_e32 v161, v69
	v_sub_f32_e32 v69, v81, v245
	v_add_f32_e32 v68, v158, v68
	v_exp_f32_e32 v162, v69
	v_sub_f32_e32 v69, v82, v245
	v_add_f32_e32 v68, v159, v68
	v_exp_f32_e32 v163, v69
	v_sub_f32_e32 v69, v83, v245
	v_add_f32_e32 v68, v160, v68
	v_exp_f32_e32 v164, v69
	v_add_f32_e32 v68, v161, v68
	v_add_f32_e32 v68, v162, v68
	v_add_f32_e32 v68, v163, v68
	v_add_f32_e32 v241, v164, v68
	v_sub_f32_e32 v68, v148, v245
	v_exp_f32_e32 v194, v68
	ds_bpermute_b32 v242, v201, v241
	v_pk_mul_f32 v[82:83], v[50:51], v[194:195] op_sel_hi:[1,0]
	v_pk_mul_f32 v[80:81], v[48:49], v[194:195] op_sel_hi:[1,0]
	v_pk_mul_f32 v[78:79], v[46:47], v[194:195] op_sel_hi:[1,0]
	v_pk_mul_f32 v[76:77], v[44:45], v[194:195] op_sel_hi:[1,0]
	v_pk_mul_f32 v[74:75], v[42:43], v[194:195] op_sel_hi:[1,0]
	v_pk_mul_f32 v[72:73], v[40:41], v[194:195] op_sel_hi:[1,0]
	v_pk_mul_f32 v[70:71], v[38:39], v[194:195] op_sel_hi:[1,0]
	v_pk_mul_f32 v[68:69], v[36:37], v[194:195] op_sel_hi:[1,0]
	v_pk_mul_f32 v[98:99], v[66:67], v[194:195] op_sel_hi:[1,0]
	v_pk_mul_f32 v[96:97], v[64:65], v[194:195] op_sel_hi:[1,0]
	v_pk_mul_f32 v[94:95], v[62:63], v[194:195] op_sel_hi:[1,0]
	v_pk_mul_f32 v[92:93], v[60:61], v[194:195] op_sel_hi:[1,0]
	v_pk_mul_f32 v[90:91], v[58:59], v[194:195] op_sel_hi:[1,0]
	v_pk_mul_f32 v[88:89], v[56:57], v[194:195] op_sel_hi:[1,0]
	v_pk_mul_f32 v[86:87], v[54:55], v[194:195] op_sel_hi:[1,0]
	v_pk_mul_f32 v[84:85], v[52:53], v[194:195] op_sel_hi:[1,0]
	v_cvt_pk_bf16_f32 v36, v149, v150
	v_cvt_pk_bf16_f32 v37, v151, v152
	v_cvt_pk_bf16_f32 v38, v153, v154
	v_cvt_pk_bf16_f32 v39, v155, v156
	s_nop 1
	v_mfma_f32_32x32x16_bf16 v[68:83], v[144:147], v[36:39], v[68:83]
	v_mfma_f32_32x32x16_bf16 v[84:99], v[140:143], v[36:39], v[84:99]
	v_cvt_pk_bf16_f32 v36, v157, v158
	v_cvt_pk_bf16_f32 v37, v159, v160
	v_cvt_pk_bf16_f32 v38, v161, v162
	v_cvt_pk_bf16_f32 v39, v163, v164
	s_nop 1
	v_mfma_f32_32x32x16_bf16 v[68:83], v[136:139], v[36:39], v[68:83]
	v_mfma_f32_32x32x16_bf16 v[84:99], v[132:135], v[36:39], v[84:99]
	v_mul_lo_u32 v36, s56, v222
	v_add_u32_e32 v40, s11, v36
	v_max_i32_e32 v164, 0, v40
	s_waitcnt vmcnt(0)
	v_lshl_add_u32 v38, v164, 7, v180
	s_mov_b32 m0, s57
	v_add_u32_e32 v40, s6, v40
	global_load_lds_dwordx4 v38, s[98:99]
	v_lshl_add_u32 v36, v164, 7, v182
	s_mov_b32 m0, s7
	v_max_i32_e32 v164, 0, v40
	global_load_lds_dwordx4 v36, s[100:101]
	v_readlane_b32 s7, v254, 28
	v_lshl_add_u32 v38, v164, 7, v180
	s_mov_b32 m0, s7
	v_readlane_b32 s7, v254, 29
	v_add_u32_e32 v40, s6, v40
	global_load_lds_dwordx4 v38, s[98:99]
	v_lshl_add_u32 v36, v164, 7, v182
	s_mov_b32 m0, s7
	v_max_i32_e32 v164, 0, v40
	global_load_lds_dwordx4 v36, s[100:101]
	v_lshl_add_u32 v38, v164, 7, v180
	s_mov_b32 m0, s15
	v_lshl_add_u32 v36, v164, 7, v182
	global_load_lds_dwordx4 v38, s[98:99]
	s_mov_b32 m0, s17
	v_sub_u32_e32 v52, v199, v223
	global_load_lds_dwordx4 v36, s[100:101]
	v_add_u32_e32 v36, s6, v40
	v_max_i32_e32 v164, 0, v36
	v_lshl_add_u32 v38, v164, 7, v180
	s_mov_b32 m0, s21
	v_readlane_b32 s6, v254, 30
	global_load_lds_dwordx4 v38, s[98:99]
	v_lshl_add_u32 v36, v164, 7, v182
	s_mov_b32 m0, s6
	v_mov_b32_e32 v53, v224
	global_load_lds_dwordx4 v36, s[100:101]
	ds_read_b128 v[160:163], v225
	ds_read_b128 v[156:159], v226
	ds_read_b128 v[152:155], v227
	ds_read_b128 v[148:151], v228
	ds_read_b64_tr_b16 v[144:145], v229 offset:8192
	ds_read_b64_tr_b16 v[146:147], v229 offset:9216
	ds_read_b64_tr_b16 v[140:141], v229 offset:8256
	ds_read_b64_tr_b16 v[142:143], v229 offset:9280
	ds_read_b64_tr_b16 v[136:137], v229 offset:10240
	ds_read_b64_tr_b16 v[138:139], v229 offset:11264
	ds_read_b64_tr_b16 v[132:133], v229 offset:10304
	ds_read_b64_tr_b16 v[134:135], v229 offset:11328
	s_waitcnt lgkmcnt(0)
; __device__ __forceinline__ unsigned pk2(float lo, float hi) { return pg8::cvt_pk_bf16(lo, hi); }
; #define ATT_LOAD_Q(dst, J, set) do { const int qp_ = (J).pos0 + (32 * (set) + qc) * (J).d; _Pragma("unroll") for (int kk_ = 0; kk_ < 4; ++kk_) dst[kk_] = gld<bf16x8>(Qa + ((J).hb + (size_t)qp_) * 64 + 8 * h + 16 * kk_); } while (0)
; __device__ __forceinline__ void att_block(const bf16x8 (&kf)[4], const bf16x8 (&qf)[4], const bf16x8 (&va)[4], f32x16& o0, f32x16& o1, float& mrun, float& lrun, bool domask, int lo_, int hi_) {
;     ...
;     for (int kk = 0; kk < 4; ++kk) st = __builtin_amdgcn_mfma_f32_32x32x16_bf16(kf[kk], qf[kk], st, 0, 0, 0);
;     if (domask) {
;         asm volatile("" : "+v"(lo_), "+v"(hi_));
; #pragma unroll
;         for (int i = 0; i < 16; ++i) { const int ci = (i & 3) + 8 * (i >> 2); st[i] = ((ci - lo_) | (hi_ - ci)) < 0 ? -INFINITY : st[i]; }
;     }
;     float bmax = -INFINITY;
; #pragma unroll
;     for (int i = 0; i < 16; ++i) bmax = fmaxf(bmax, st[i]);
;     bmax = fmaxf(bmax, __shfl_xor(bmax, 32));
;     const float mnew = fmaxf(mrun, bmax);
;     float lsum = 0.f;
; #pragma unroll
;     for (int i = 0; i < 16; ++i) { st[i] = __builtin_amdgcn_exp2f(st[i] - mnew); lsum += st[i]; }
;     lsum += __shfl_xor(lsum, 32);
;     const float alpha = __builtin_amdgcn_exp2f(mrun - mnew);
;     lrun = lrun * alpha + lsum; mrun = mnew;
; #pragma unroll
;     for (int i = 0; i < 16; ++i) { o0[i] *= alpha; o1[i] *= alpha; }
; #pragma unroll
;     for (int s = 0; s < 2; ++s) { v4u w; w.x = pk2(st[8 * s], st[8 * s + 1]); w.y = pk2(st[8 * s + 2], st[8 * s + 3]); w.z = pk2(st[8 * s + 4], st[8 * s + 5]); w.w = pk2(st[8 * s + 6], st[8 * s + 7]);
;         const bf16x8 pb = __builtin_bit_cast(bf16x8, w);
;         o0 = __builtin_amdgcn_mfma_f32_32x32x16_bf16(va[2 * s], pb, o0, 0, 0, 0);
;         o1 = __builtin_amdgcn_mfma_f32_32x32x16_bf16(va[2 * s + 1], pb, o1, 0, 0, 0); }
; __device__ __forceinline__ void att_phase(unsigned char* ws, LAS unsigned char* lds, int lane, int wave, int G) {
;     ...
;             if (kb <= 4) {
;                 att_block(kf, qfA, va, oA0, oA1, mA, lA, kb == 0 || kb == 4 || kminA > 32 * kb, mloA - 4 * h - 32 * kb, qc + 128 - 4 * h - 32 * kb);
;                 if (kb == 4 && hn) ATT_LOAD_Q(qfA, N, 0);
	v_mfma_f32_32x32x16_bf16 v[36:51], v[160:163], v[128:131], 0
	s_nop 0
	v_mfma_f32_32x32x16_bf16 v[36:51], v[156:159], v[124:127], v[36:51]
	v_mfma_f32_32x32x16_bf16 v[36:51], v[152:155], v[120:123], v[36:51]
	v_mfma_f32_32x32x16_bf16 v[36:51], v[148:151], v[116:119], v[36:51]
	s_nop 11
	s_mov_b32 vcc_lo, 0xffffffff
	s_mov_b32 vcc_hi, 0xfffffff0
	s_mov_b32 s24, 0xfffffffe
	s_mov_b32 s25, 0xffffffe0
	s_mov_b32 s26, 0xfffffffc
	s_mov_b32 s27, 0xffffffc0
	s_mov_b32 s28, 0xfffffff8
	s_mov_b32 s29, 0xffffff80
	v_cndmask_b32_e32 v36, v211, v36, vcc
	s_mov_b32 vcc_lo, 0xffffff00
	s_mov_b32 vcc_hi, 0xfffff000
	v_cndmask_b32_e64 v37, v211, v37, s[24:25]
	s_mov_b32 s24, 0xfffffe00
	s_mov_b32 s25, 0xffffe000
	v_cndmask_b32_e64 v38, v211, v38, s[26:27]
	s_mov_b32 s26, 0xfffffc00
	s_mov_b32 s27, 0xffffc000
	v_cndmask_b32_e64 v39, v211, v39, s[28:29]
	s_mov_b32 s28, 0xfffff800
	s_mov_b32 s29, 0xffff8000
	v_cndmask_b32_e32 v40, v211, v40, vcc
	s_mov_b32 vcc_lo, 0xffff0000
	s_mov_b32 vcc_hi, 0xfff00000
	v_cndmask_b32_e64 v41, v211, v41, s[24:25]
	s_mov_b32 s24, 0xfffe0000
	s_mov_b32 s25, 0xffe00000
	v_cndmask_b32_e64 v42, v211, v42, s[26:27]
	s_mov_b32 s26, 0xfffc0000
	s_mov_b32 s27, 0xffc00000
	v_cndmask_b32_e64 v43, v211, v43, s[28:29]
	s_mov_b32 s28, 0xfff80000
	s_mov_b32 s29, 0xff800000
	v_cndmask_b32_e32 v44, v211, v44, vcc
	s_mov_b32 vcc_lo, 0xff000000
	s_mov_b32 vcc_hi, 0xf0000000
	v_cndmask_b32_e64 v45, v211, v45, s[24:25]
	s_mov_b32 s24, 0xfe000000
	s_mov_b32 s25, 0xe0000000
	v_cndmask_b32_e64 v46, v211, v46, s[26:27]
	s_mov_b32 s26, 0xfc000000
	s_mov_b32 s27, 0xc0000000
	v_cndmask_b32_e64 v47, v211, v47, s[28:29]
	s_mov_b32 s28, 0xf8000000
	s_mov_b32 s29, 0x80000000
	v_cndmask_b32_e32 v48, v211, v48, vcc
	v_cndmask_b32_e64 v49, v211, v49, s[24:25]
	v_cndmask_b32_e64 v50, v211, v50, s[26:27]
	v_cndmask_b32_e64 v51, v211, v51, s[28:29]
	s_nop 0
	v_max3_f32 v52, v36, s58, v37
	v_max3_f32 v52, v52, v38, v39
	v_max3_f32 v52, v52, v40, v41
	v_max3_f32 v52, v52, v42, v43
	v_max3_f32 v52, v52, v44, v45
	v_max3_f32 v52, v52, v46, v47
	v_max3_f32 v52, v52, v48, v49
	v_max3_f32 v52, v52, v50, v51
	ds_bpermute_b32 v53, v201, v52
	s_andn2_b64 vcc, exec, s[2:3]
	s_waitcnt lgkmcnt(0)
	v_max3_f32 v200, v202, v52, v53
	v_sub_f32_e32 v36, v36, v200
	v_exp_f32_e32 v164, v36
	v_sub_f32_e32 v37, v37, v200
	v_exp_f32_e32 v166, v37
	v_sub_f32_e32 v37, v38, v200
	v_exp_f32_e32 v167, v37
	v_sub_f32_e32 v37, v39, v200
	v_exp_f32_e32 v199, v37
	v_sub_f32_e32 v37, v40, v200
	v_exp_f32_e32 v248, v37
	v_sub_f32_e32 v37, v41, v200
	v_add_f32_e32 v36, v166, v164
	v_exp_f32_e32 v249, v37
	v_sub_f32_e32 v37, v42, v200
	v_add_f32_e32 v36, v167, v36
	v_exp_f32_e32 v250, v37
	v_sub_f32_e32 v37, v43, v200
	v_add_f32_e32 v36, v199, v36
	v_exp_f32_e32 v251, v37
	v_sub_f32_e32 v37, v44, v200
	v_add_f32_e32 v36, v248, v36
	v_exp_f32_e32 v252, v37
	v_sub_f32_e32 v37, v45, v200
	v_add_f32_e32 v36, v249, v36
	v_exp_f32_e32 v203, v37
	v_sub_f32_e32 v37, v46, v200
	v_add_f32_e32 v36, v250, v36
	v_exp_f32_e32 v168, v37
	v_sub_f32_e32 v37, v47, v200
	v_add_f32_e32 v36, v251, v36
	v_exp_f32_e32 v169, v37
	v_sub_f32_e32 v37, v48, v200
	v_add_f32_e32 v36, v252, v36
	v_exp_f32_e32 v212, v37
	v_sub_f32_e32 v37, v49, v200
	v_add_f32_e32 v36, v203, v36
	v_exp_f32_e32 v209, v37
	v_sub_f32_e32 v37, v50, v200
	v_add_f32_e32 v36, v168, v36
	v_exp_f32_e32 v197, v37
	v_sub_f32_e32 v37, v51, v200
	v_add_f32_e32 v36, v169, v36
	v_exp_f32_e32 v195, v37
	v_add_f32_e32 v36, v212, v36
	v_add_f32_e32 v36, v209, v36
	v_add_f32_e32 v36, v197, v36
	v_add_f32_e32 v246, v195, v36
	v_sub_f32_e32 v36, v202, v200
	v_exp_f32_e32 v202, v36
	ds_bpermute_b32 v247, v201, v246
	v_pk_mul_f32 v[66:67], v[18:19], v[202:203] op_sel_hi:[1,0]
	v_pk_mul_f32 v[64:65], v[16:17], v[202:203] op_sel_hi:[1,0]
	v_pk_mul_f32 v[62:63], v[14:15], v[202:203] op_sel_hi:[1,0]
	v_pk_mul_f32 v[60:61], v[12:13], v[202:203] op_sel_hi:[1,0]
	v_pk_mul_f32 v[58:59], v[10:11], v[202:203] op_sel_hi:[1,0]
	v_pk_mul_f32 v[56:57], v[8:9], v[202:203] op_sel_hi:[1,0]
	v_pk_mul_f32 v[54:55], v[6:7], v[202:203] op_sel_hi:[1,0]
	v_pk_mul_f32 v[52:53], v[4:5], v[202:203] op_sel_hi:[1,0]
	v_pk_mul_f32 v[50:51], v[34:35], v[202:203] op_sel_hi:[1,0]
	v_pk_mul_f32 v[48:49], v[32:33], v[202:203] op_sel_hi:[1,0]
	v_pk_mul_f32 v[46:47], v[30:31], v[202:203] op_sel_hi:[1,0]
	v_pk_mul_f32 v[44:45], v[28:29], v[202:203] op_sel_hi:[1,0]
	v_pk_mul_f32 v[42:43], v[26:27], v[202:203] op_sel_hi:[1,0]
	v_pk_mul_f32 v[40:41], v[24:25], v[202:203] op_sel_hi:[1,0]
	v_pk_mul_f32 v[38:39], v[22:23], v[202:203] op_sel_hi:[1,0]
	v_pk_mul_f32 v[36:37], v[20:21], v[202:203] op_sel_hi:[1,0]
	v_cvt_pk_bf16_f32 v4, v164, v166
	v_cvt_pk_bf16_f32 v5, v167, v199
	v_cvt_pk_bf16_f32 v6, v248, v249
	v_cvt_pk_bf16_f32 v7, v250, v251
	s_nop 1
	v_mfma_f32_32x32x16_bf16 v[52:67], v[144:147], v[4:7], v[52:67]
	v_mfma_f32_32x32x16_bf16 v[36:51], v[140:143], v[4:7], v[36:51]
	v_cvt_pk_bf16_f32 v4, v252, v203
	v_cvt_pk_bf16_f32 v5, v168, v169
	v_cvt_pk_bf16_f32 v6, v212, v209
	v_cvt_pk_bf16_f32 v7, v197, v195
	s_nop 1
	v_mfma_f32_32x32x16_bf16 v[52:67], v[136:139], v[4:7], v[52:67]
	v_mfma_f32_32x32x16_bf16 v[36:51], v[132:135], v[4:7], v[36:51]
	v_cndmask_b32_e64 v4, 0, 1, s[2:3]
	v_cmp_ne_u32_e64 s[6:7], 1, v4
	s_cbranch_vccnz .LBB0_92
	v_ashrrev_i32_e32 v199, 31, v198
	v_lshl_add_u64 v[4:5], s[0:1], 0, v[198:199]
	v_lshlrev_b64 v[4:5], 7, v[4:5]
	v_lshl_add_u64 v[4:5], v[186:187], 0, v[4:5]
	global_load_dwordx4 v[128:131], v[4:5], off
	global_load_dwordx4 v[124:127], v[4:5], off offset:32
	global_load_dwordx4 v[120:123], v[4:5], off offset:64
	global_load_dwordx4 v[116:119], v[4:5], off offset:96

; __device__ __forceinline__ unsigned pk2(float lo, float hi) { return pg8::cvt_pk_bf16(lo, hi); }
; __device__ __forceinline__ void att_block(const bf16x8 (&kf)[4], const bf16x8 (&qf)[4], const bf16x8 (&va)[4], f32x16& o0, f32x16& o1, float& mrun, float& lrun, bool domask, int lo_, int hi_) {
;     ...
;     float bmax = -INFINITY;
; #pragma unroll
;     for (int i = 0; i < 16; ++i) bmax = fmaxf(bmax, st[i]);
;     bmax = fmaxf(bmax, __shfl_xor(bmax, 32));
;     const float mnew = fmaxf(mrun, bmax);
;     float lsum = 0.f;
; #pragma unroll
;     for (int i = 0; i < 16; ++i) { st[i] = __builtin_amdgcn_exp2f(st[i] - mnew); lsum += st[i]; }
;     lsum += __shfl_xor(lsum, 32);
;     const float alpha = __builtin_amdgcn_exp2f(mrun - mnew);
;     lrun = lrun * alpha + lsum; mrun = mnew;
; #pragma unroll
;     for (int i = 0; i < 16; ++i) { o0[i] *= alpha; o1[i] *= alpha; }
; #pragma unroll
;     for (int s = 0; s < 2; ++s) { v4u w; w.x = pk2(st[8 * s], st[8 * s + 1]); w.y = pk2(st[8 * s + 2], st[8 * s + 3]); w.z = pk2(st[8 * s + 4], st[8 * s + 5]); w.w = pk2(st[8 * s + 6], st[8 * s + 7]);
;         const bf16x8 pb = __builtin_bit_cast(bf16x8, w);
;         o0 = __builtin_amdgcn_mfma_f32_32x32x16_bf16(va[2 * s], pb, o0, 0, 0, 0);
;         o1 = __builtin_amdgcn_mfma_f32_32x32x16_bf16(va[2 * s + 1], pb, o1, 0, 0, 0); }
; __device__ __forceinline__ void att_phase(unsigned char* ws, LAS unsigned char* lds, int lane, int wave, int G) {
;     ...
;             asm volatile("s_waitcnt vmcnt(0)" ::: "memory");
;             if (kb < 5) ATT_DMA_KV(P, kb + 1, sb ^ 1);
;             else if (hn) ATT_DMA_KV(N, 0, sb ^ 1);
.LBB0_94:
	s_mov_b32 s14, 0xff800000
	s_nop 9
	v_max3_f32 v20, v4, s14, v5
	v_max3_f32 v20, v20, v6, v7
	v_max3_f32 v20, v20, v8, v9
	v_max3_f32 v20, v20, v10, v11
	v_max3_f32 v20, v20, v12, v13
	v_max3_f32 v20, v20, v14, v15
	v_max3_f32 v20, v20, v16, v17
	v_max3_f32 v20, v20, v18, v19
	ds_bpermute_b32 v21, v201, v20
	s_waitcnt lgkmcnt(0)
	s_waitcnt lgkmcnt(0)
	v_max3_f32 v151, v245, v20, v21
	v_sub_f32_e32 v4, v4, v151
	v_exp_f32_e32 v152, v4
	v_sub_f32_e32 v5, v5, v151
	v_exp_f32_e32 v153, v5
	v_sub_f32_e32 v5, v6, v151
	v_exp_f32_e32 v154, v5
	v_sub_f32_e32 v5, v7, v151
	v_exp_f32_e32 v155, v5
	v_sub_f32_e32 v5, v8, v151
	v_exp_f32_e32 v156, v5
	v_sub_f32_e32 v5, v9, v151
	v_add_f32_e32 v4, v153, v152
	v_exp_f32_e32 v157, v5
	v_sub_f32_e32 v5, v10, v151
	v_add_f32_e32 v4, v154, v4
	v_exp_f32_e32 v158, v5
	v_sub_f32_e32 v5, v11, v151
	v_add_f32_e32 v4, v155, v4
	v_exp_f32_e32 v159, v5
	v_sub_f32_e32 v5, v12, v151
	v_add_f32_e32 v4, v156, v4
	v_exp_f32_e32 v160, v5
	v_sub_f32_e32 v5, v13, v151
	v_add_f32_e32 v4, v157, v4
	v_exp_f32_e32 v161, v5
	v_sub_f32_e32 v5, v14, v151
	v_add_f32_e32 v4, v158, v4
	v_exp_f32_e32 v162, v5
	v_sub_f32_e32 v5, v15, v151
	v_add_f32_e32 v4, v159, v4
	v_exp_f32_e32 v163, v5
	v_sub_f32_e32 v5, v16, v151
	v_add_f32_e32 v4, v160, v4
	v_exp_f32_e32 v164, v5
	v_sub_f32_e32 v5, v17, v151
	v_add_f32_e32 v4, v161, v4
	v_exp_f32_e32 v166, v5
	v_sub_f32_e32 v5, v18, v151
	v_add_f32_e32 v4, v162, v4
	v_exp_f32_e32 v167, v5
	v_sub_f32_e32 v5, v19, v151
	v_add_f32_e32 v4, v163, v4
	v_exp_f32_e32 v168, v5
	v_add_f32_e32 v4, v164, v4
	v_add_f32_e32 v4, v166, v4
	v_add_f32_e32 v4, v167, v4
	v_add_f32_e32 v149, v168, v4
	v_sub_f32_e32 v4, v245, v151
	v_exp_f32_e32 v148, v4
	ds_bpermute_b32 v150, v201, v149
	v_pk_mul_f32 v[34:35], v[82:83], v[148:149] op_sel_hi:[1,0]
	v_pk_mul_f32 v[32:33], v[80:81], v[148:149] op_sel_hi:[1,0]
	v_pk_mul_f32 v[30:31], v[78:79], v[148:149] op_sel_hi:[1,0]
	v_pk_mul_f32 v[28:29], v[76:77], v[148:149] op_sel_hi:[1,0]
	v_pk_mul_f32 v[26:27], v[74:75], v[148:149] op_sel_hi:[1,0]
	v_pk_mul_f32 v[24:25], v[72:73], v[148:149] op_sel_hi:[1,0]
	v_pk_mul_f32 v[22:23], v[70:71], v[148:149] op_sel_hi:[1,0]
	v_pk_mul_f32 v[20:21], v[68:69], v[148:149] op_sel_hi:[1,0]
	v_pk_mul_f32 v[18:19], v[98:99], v[148:149] op_sel_hi:[1,0]
	v_pk_mul_f32 v[16:17], v[96:97], v[148:149] op_sel_hi:[1,0]
	v_pk_mul_f32 v[14:15], v[94:95], v[148:149] op_sel_hi:[1,0]
	v_pk_mul_f32 v[12:13], v[92:93], v[148:149] op_sel_hi:[1,0]
	v_pk_mul_f32 v[10:11], v[90:91], v[148:149] op_sel_hi:[1,0]
	v_pk_mul_f32 v[8:9], v[88:89], v[148:149] op_sel_hi:[1,0]
	v_pk_mul_f32 v[6:7], v[86:87], v[148:149] op_sel_hi:[1,0]
	v_pk_mul_f32 v[4:5], v[84:85], v[148:149] op_sel_hi:[1,0]
	v_cvt_pk_bf16_f32 v68, v152, v153
	v_cvt_pk_bf16_f32 v69, v154, v155
	v_cvt_pk_bf16_f32 v70, v156, v157
	v_cvt_pk_bf16_f32 v71, v158, v159
	s_nop 1
	v_mfma_f32_32x32x16_bf16 v[20:35], v[144:147], v[68:71], v[20:35]
	v_mfma_f32_32x32x16_bf16 v[4:19], v[140:143], v[68:71], v[4:19]
	v_cvt_pk_bf16_f32 v68, v160, v161
	v_cvt_pk_bf16_f32 v69, v162, v163
	v_cvt_pk_bf16_f32 v70, v164, v166
	v_cvt_pk_bf16_f32 v71, v167, v168
	s_nop 1
	v_mfma_f32_32x32x16_bf16 v[20:35], v[136:139], v[68:71], v[20:35]
	v_mfma_f32_32x32x16_bf16 v[4:19], v[132:135], v[68:71], v[4:19]
	s_waitcnt vmcnt(0)
	s_and_b64 vcc, exec, s[6:7]
	s_cbranch_vccnz .LBB0_96
	v_add_u32_e32 v68, 0xffffff80, v191
	v_mul_lo_u32 v68, s52, v68
	v_add_u32_e32 v72, s53, v68
	v_max_i32_e32 v164, 0, v72
	s_lshl_b32 s14, s52, 3
	s_mov_b32 m0, s33
	v_lshl_add_u32 v70, v164, 7, v180
	v_add_u32_e32 v72, s14, v72
	global_load_lds_dwordx4 v70, s[30:31]
	v_lshl_add_u32 v68, v164, 7, v182
	s_mov_b32 m0, s44
	v_max_i32_e32 v164, 0, v72
	global_load_lds_dwordx4 v68, s[34:35]
	v_lshl_add_u32 v70, v164, 7, v180
	s_mov_b32 m0, s66
	v_add_u32_e32 v72, s14, v72
	global_load_lds_dwordx4 v70, s[30:31]
	v_lshl_add_u32 v68, v164, 7, v182
	s_mov_b32 m0, s67
	v_max_i32_e32 v164, 0, v72
	global_load_lds_dwordx4 v68, s[34:35]
	v_lshl_add_u32 v70, v164, 7, v180
	s_mov_b32 m0, s48
	v_lshl_add_u32 v68, v164, 7, v182
	global_load_lds_dwordx4 v70, s[30:31]
	s_mov_b32 m0, s49
	s_nop 0
	global_load_lds_dwordx4 v68, s[34:35]
	v_add_u32_e32 v68, s14, v72
	v_max_i32_e32 v164, 0, v68
	v_lshl_add_u32 v70, v164, 7, v180
	s_mov_b32 m0, s72
	v_readlane_b32 s14, v254, 27
	global_load_lds_dwordx4 v70, s[30:31]
	v_lshl_add_u32 v68, v164, 7, v182
	s_mov_b32 m0, s14
	s_nop 0
	global_load_lds_dwordx4 v68, s[34:35]
; __device__ __forceinline__ void att_block(const bf16x8 (&kf)[4], const bf16x8 (&qf)[4], const bf16x8 (&va)[4], f32x16& o0, f32x16& o1, float& mrun, float& lrun, bool domask, int lo_, int hi_) {
;     f32x16 st;
; #pragma unroll
;     for (int i = 0; i < 16; ++i) st[i] = 0.f;
; #pragma unroll
;     for (int kk = 0; kk < 4; ++kk) st = __builtin_amdgcn_mfma_f32_32x32x16_bf16(kf[kk], qf[kk], st, 0, 0, 0);
;     if (domask) {
;         asm volatile("" : "+v"(lo_), "+v"(hi_));
; #pragma unroll
;         for (int i = 0; i < 16; ++i) { const int ci = (i & 3) + 8 * (i >> 2); st[i] = ((ci - lo_) | (hi_ - ci)) < 0 ? -INFINITY : st[i]; }
;     }
;     float bmax = -INFINITY;
; #pragma unroll
;     for (int i = 0; i < 16; ++i) bmax = fmaxf(bmax, st[i]);
;     bmax = fmaxf(bmax, __shfl_xor(bmax, 32));
;     const float mnew = fmaxf(mrun, bmax);
;     float lsum = 0.f;
; #pragma unroll
;     for (int i = 0; i < 16; ++i) { st[i] = __builtin_amdgcn_exp2f(st[i] - mnew); lsum += st[i]; }
;     lsum += __shfl_xor(lsum, 32);
; __device__ __forceinline__ void att_phase(unsigned char* ws, LAS unsigned char* lds, int lane, int wave, int G) {
;     ...
;             bf16x8 kf[4], va[4];
; #pragma unroll
;             for (int kk = 0; kk < 4; ++kk) kf[kk] = *(LAS const bf16x8*)(kfb + sb * 4096 + (((2 * kk + h) ^ (qc & 7)) << 4));
;             LAS const unsigned char* trs = trb + 8192 + sb * 4096;
; #pragma unroll
;             for (int s = 0; s < 2; ++s) {
;                 const s16x4 lo0 = vtr(trs + (16 * s) * VP), hi0 = vtr(trs + (16 * s + 8) * VP);
;                 const s16x4 lo1 = vtr(trs + (16 * s) * VP + 64), hi1 = vtr(trs + (16 * s + 8) * VP + 64);
;                 va[2 * s] = (bf16x8){lo0[0], lo0[1], lo0[2], lo0[3], hi0[0], hi0[1], hi0[2], hi0[3]};
;                 va[2 * s + 1] = (bf16x8){lo1[0], lo1[1], lo1[2], lo1[3], hi1[0], hi1[1], hi1[2], hi1[3]};
;             }
;             if (kb <= 4) {
;                 att_block(kf, qfA, va, oA0, oA1, mA, lA, kb == 0 || kb == 4 || kminA > 32 * kb, mloA - 4 * h - 32 * kb, qc + 128 - 4 * h - 32 * kb);
;                 if (kb == 4 && hn) ATT_LOAD_Q(qfA, N, 0);
;             }
;             if (kb >= 1) {
;                 att_block(kf, qfB, va, oB0, oB1, mB, lB, kb == 1 || kb == 5 || kminB > 32 * (kb - 1), mloB - 4 * h - 32 * (kb - 1), qc + 128 - 4 * h - 32 * (kb - 1));
;                 if (kb == 5 && hn) ATT_LOAD_Q(qfB, N, 1);
.LBB0_96:
	ds_read_b128 v[68:71], v225 offset:4096
	ds_read_b128 v[132:135], v226 offset:4096
	ds_read_b128 v[136:139], v227 offset:4096
	ds_read_b128 v[140:143], v228 offset:4096
	ds_read_b64_tr_b16 v[92:93], v229 offset:12288
	ds_read_b64_tr_b16 v[94:95], v229 offset:13312
	ds_read_b64_tr_b16 v[86:87], v229 offset:13376
	ds_read_b64_tr_b16 v[84:85], v229 offset:12352
	s_waitcnt lgkmcnt(0)
	v_mfma_f32_32x32x16_bf16 v[68:83], v[68:71], v[112:115], 0
	v_sub_u32_e32 v144, v237, v223
	v_mov_b32_e32 v145, v224
	ds_read_b64_tr_b16 v[96:97], v229 offset:14336
	ds_read_b64_tr_b16 v[98:99], v229 offset:15360
	ds_read_b64_tr_b16 v[90:91], v229 offset:15424
	ds_read_b64_tr_b16 v[88:89], v229 offset:14400
	s_mov_b32 s14, 0xff800000
	v_mfma_f32_32x32x16_bf16 v[68:83], v[132:135], v[108:111], v[68:83]
	v_mfma_f32_32x32x16_bf16 v[68:83], v[136:139], v[104:107], v[68:83]
	v_mfma_f32_32x32x16_bf16 v[68:83], v[140:143], v[100:103], v[68:83]
	s_nop 11
	s_mov_b32 vcc_lo, 0xffffffff
	s_mov_b32 vcc_hi, 0xfffffff0
	s_mov_b32 s24, 0xfffffffe
	s_mov_b32 s25, 0xffffffe0
	s_mov_b32 s26, 0xfffffffc
	s_mov_b32 s27, 0xffffffc0
	s_mov_b32 s28, 0xfffffff8
	s_mov_b32 s29, 0xffffff80
	v_cndmask_b32_e32 v68, v211, v68, vcc
	s_mov_b32 vcc_lo, 0xffffff00
	s_mov_b32 vcc_hi, 0xfffff000
	v_cndmask_b32_e64 v69, v211, v69, s[24:25]
	s_mov_b32 s24, 0xfffffe00
	s_mov_b32 s25, 0xffffe000
	v_cndmask_b32_e64 v70, v211, v70, s[26:27]
	s_mov_b32 s26, 0xfffffc00
	s_mov_b32 s27, 0xffffc000
	v_cndmask_b32_e64 v71, v211, v71, s[28:29]
	s_mov_b32 s28, 0xfffff800
	s_mov_b32 s29, 0xffff8000
	v_cndmask_b32_e32 v72, v211, v72, vcc
	s_mov_b32 vcc_lo, 0xffff0000
	s_mov_b32 vcc_hi, 0xfff00000
	v_cndmask_b32_e64 v73, v211, v73, s[24:25]
	s_mov_b32 s24, 0xfffe0000
	s_mov_b32 s25, 0xffe00000
	v_cndmask_b32_e64 v74, v211, v74, s[26:27]
	s_mov_b32 s26, 0xfffc0000
	s_mov_b32 s27, 0xffc00000
	v_cndmask_b32_e64 v75, v211, v75, s[28:29]
	s_mov_b32 s28, 0xfff80000
	s_mov_b32 s29, 0xff800000
	v_cndmask_b32_e32 v132, v211, v76, vcc
	s_mov_b32 vcc_lo, 0xff000000
	s_mov_b32 vcc_hi, 0xf0000000
	v_cndmask_b32_e64 v77, v211, v77, s[24:25]
	s_mov_b32 s24, 0xfe000000
	s_mov_b32 s25, 0xe0000000
	v_cndmask_b32_e64 v78, v211, v78, s[26:27]
	s_mov_b32 s26, 0xfc000000
	s_mov_b32 s27, 0xc0000000
	v_cndmask_b32_e64 v79, v211, v79, s[28:29]
	s_mov_b32 s28, 0xf8000000
	s_mov_b32 s29, 0x80000000
	v_cndmask_b32_e32 v80, v211, v80, vcc
	v_cndmask_b32_e64 v81, v211, v81, s[24:25]
	v_cndmask_b32_e64 v82, v211, v82, s[26:27]
	v_cndmask_b32_e64 v83, v211, v83, s[28:29]
	s_nop 0
	s_nop 1
	s_nop 1
	s_nop 0
	v_max3_f32 v76, v68, s14, v69
	v_max3_f32 v76, v76, v70, v71
	v_max3_f32 v76, v76, v72, v73
	v_max3_f32 v76, v76, v74, v75
	v_max3_f32 v76, v76, v132, v77
	v_max3_f32 v76, v76, v78, v79
	v_max3_f32 v76, v76, v80, v81
	v_max3_f32 v76, v76, v82, v83
	ds_bpermute_b32 v133, v201, v76
	s_and_b64 vcc, exec, s[6:7]
	s_waitcnt lgkmcnt(0)
	v_max3_f32 v76, v151, v76, v133
	v_sub_f32_e32 v68, v68, v76
	v_exp_f32_e32 v68, v68
	v_sub_f32_e32 v69, v69, v76
	v_exp_f32_e32 v69, v69
	v_sub_f32_e32 v70, v70, v76
	v_exp_f32_e32 v70, v70
	v_sub_f32_e32 v71, v71, v76
	v_exp_f32_e32 v71, v71
	v_sub_f32_e32 v72, v72, v76
	v_exp_f32_e32 v72, v72
	v_sub_f32_e32 v73, v73, v76
	v_add_f32_e32 v133, v69, v68
	v_exp_f32_e32 v73, v73
	v_sub_f32_e32 v74, v74, v76
	v_add_f32_e32 v133, v70, v133
	v_exp_f32_e32 v74, v74
	v_sub_f32_e32 v75, v75, v76
	v_add_f32_e32 v133, v71, v133
	v_exp_f32_e32 v75, v75
	v_sub_f32_e32 v132, v132, v76
	v_add_f32_e32 v133, v72, v133
	v_exp_f32_e32 v132, v132
	v_sub_f32_e32 v77, v77, v76
	v_add_f32_e32 v133, v73, v133
	v_exp_f32_e32 v77, v77
	v_sub_f32_e32 v78, v78, v76
	v_add_f32_e32 v133, v74, v133
	v_exp_f32_e32 v134, v78
	v_add_f32_e32 v78, v75, v133
	v_add_f32_e32 v78, v132, v78
	v_add_f32_e32 v78, v77, v78
	v_add_f32_e32 v133, v134, v78
	v_sub_f32_e32 v78, v79, v76
	v_exp_f32_e32 v79, v78
	v_sub_f32_e32 v78, v80, v76
	v_exp_f32_e32 v80, v78
	v_sub_f32_e32 v78, v151, v76
	v_exp_f32_e32 v78, v78
	v_cvt_pk_bf16_f32 v68, v68, v69
	v_cvt_pk_bf16_f32 v69, v70, v71
	v_cvt_pk_bf16_f32 v70, v72, v73
	v_pk_mul_f32 v[34:35], v[34:35], v[78:79] op_sel_hi:[1,0]
	v_pk_mul_f32 v[32:33], v[32:33], v[78:79] op_sel_hi:[1,0]
	v_pk_mul_f32 v[30:31], v[30:31], v[78:79] op_sel_hi:[1,0]
	v_pk_mul_f32 v[28:29], v[28:29], v[78:79] op_sel_hi:[1,0]
	v_pk_mul_f32 v[26:27], v[26:27], v[78:79] op_sel_hi:[1,0]
	v_pk_mul_f32 v[24:25], v[24:25], v[78:79] op_sel_hi:[1,0]
	v_pk_mul_f32 v[22:23], v[22:23], v[78:79] op_sel_hi:[1,0]
	v_pk_mul_f32 v[20:21], v[20:21], v[78:79] op_sel_hi:[1,0]
	v_pk_mul_f32 v[18:19], v[18:19], v[78:79] op_sel_hi:[1,0]
	v_cvt_pk_bf16_f32 v71, v74, v75
	v_pk_mul_f32 v[16:17], v[16:17], v[78:79] op_sel_hi:[1,0]
	v_pk_mul_f32 v[14:15], v[14:15], v[78:79] op_sel_hi:[1,0]
	v_pk_mul_f32 v[12:13], v[12:13], v[78:79] op_sel_hi:[1,0]
	v_pk_mul_f32 v[10:11], v[10:11], v[78:79] op_sel_hi:[1,0]
	v_pk_mul_f32 v[8:9], v[8:9], v[78:79] op_sel_hi:[1,0]
	v_pk_mul_f32 v[6:7], v[6:7], v[78:79] op_sel_hi:[1,0]
	v_pk_mul_f32 v[4:5], v[4:5], v[78:79] op_sel_hi:[1,0]
	v_mfma_f32_32x32x16_bf16 v[20:35], v[92:95], v[68:71], v[20:35]
	v_sub_f32_e32 v81, v81, v76
	v_sub_f32_e32 v82, v82, v76
	v_exp_f32_e32 v81, v81
	v_exp_f32_e32 v72, v82
	v_add_f32_e32 v74, v79, v133
	v_add_f32_e32 v74, v80, v74
	v_add_f32_e32 v74, v81, v74
	v_mfma_f32_32x32x16_bf16 v[4:19], v[84:87], v[68:71], v[4:19]
	v_sub_f32_e32 v68, v83, v76
	v_exp_f32_e32 v73, v68
	v_cvt_pk_bf16_f32 v68, v132, v77
	v_cvt_pk_bf16_f32 v69, v134, v79
	v_cvt_pk_bf16_f32 v70, v80, v81
	v_cvt_pk_bf16_f32 v71, v72, v73
	v_add_f32_e32 v72, v72, v74
	v_add_f32_e32 v77, v73, v72
	v_mfma_f32_32x32x16_bf16 v[20:35], v[96:99], v[68:71], v[20:35]
	ds_bpermute_b32 v79, v201, v77
	v_mfma_f32_32x32x16_bf16 v[4:19], v[88:91], v[68:71], v[4:19]
	s_cbranch_vccnz .LBB0_98
	v_lshl_add_u32 v68, s52, 5, v198
	v_ashrrev_i32_e32 v69, 31, v68
	v_lshl_add_u64 v[68:69], s[0:1], 0, v[68:69]
	v_lshlrev_b64 v[68:69], 7, v[68:69]
	v_lshl_add_u64 v[68:69], v[186:187], 0, v[68:69]
	global_load_dwordx4 v[112:115], v[68:69], off
	global_load_dwordx4 v[108:111], v[68:69], off offset:32
	global_load_dwordx4 v[104:107], v[68:69], off offset:64
	global_load_dwordx4 v[100:103], v[68:69], off offset:96
